# v17 + write-through stores also in residual GEMM epilogue (H), start_row and elementwise prep/merge/combine phases
# baseline (speedup 1.0000x reference)
; DI unsigned pk2(float lo, float hi) { f32x2 v = {lo, hi}; bf16x2_t b = __builtin_convertvector(v, bf16x2_t); return __builtin_bit_cast(unsigned, b); }
; DI float bflo(unsigned w) { return __uint_as_float(w << 16); }
; DI float bfhi(unsigned w) { return __uint_as_float(w & 0xffff0000u); }
; DI void start_row(const float* xrow, bf16_t* brow, unsigned long long* ssp, int lane) {
;     const __attribute__((address_space(1))) f32x4* xr = (const __attribute__((address_space(1))) f32x4*)xrow + lane; __attribute__((address_space(1))) u32x2* o8 = (__attribute__((address_space(1))) u32x2*)brow + lane;
;     float s = 0.f;
;     f32x4 vv[4];
; #pragma unroll
;     for (int j = 0; j < 4; ++j) vv[j] = __builtin_nontemporal_load(xr + 64 * j);
; #pragma unroll
;     for (int j = 0; j < 4; ++j) { const f32x4 v = vv[j]; u32x2 w; w.x = pk2(v.x, v.y); w.y = pk2(v.z, v.w); o8[64 * j] = w;
;         const float a = bflo(w.x), b = bfhi(w.x), c = bflo(w.y), d = bfhi(w.y); s += (a * a + b * b) + (c * c + d * d); }
;     s = wave_sum(s);
;     if (lane == 0) *(__attribute__((address_space(1))) unsigned long long*)ssp = (unsigned long long)(s * 1048576.0f + 0.5f);
; }
.LBB0_15:
	s_waitcnt lgkmcnt(0)
	global_load_dwordx4 v[8:11], v6, s[4:5] nt
	global_load_dwordx4 v[12:15], v6, s[4:5] offset:1024 nt
	global_load_dwordx4 v[16:19], v6, s[4:5] offset:2048 nt
	global_load_dwordx4 v[20:23], v6, s[4:5] offset:3072 nt
	s_waitcnt vmcnt(0)
	v_cvt_pk_bf16_f32 v24, v8, v9
	v_cvt_pk_bf16_f32 v25, v10, v11
	s_waitcnt vmcnt(2)
	v_cvt_pk_bf16_f32 v10, v12, v13
	v_cvt_pk_bf16_f32 v11, v14, v15
	s_waitcnt vmcnt(1)
	v_cvt_pk_bf16_f32 v12, v16, v17
	v_cvt_pk_bf16_f32 v13, v18, v19
	s_waitcnt vmcnt(0)
	v_cvt_pk_bf16_f32 v14, v20, v21
	v_and_b32_e32 v9, 0xffff0000, v24
	v_and_b32_e32 v17, 0xffff0000, v25
	v_and_b32_e32 v19, 0xffff0000, v10
	v_and_b32_e32 v21, 0xffff0000, v11
	v_cvt_pk_bf16_f32 v15, v22, v23
	v_lshlrev_b32_e32 v8, 16, v24
	v_lshlrev_b32_e32 v16, 16, v25
	v_lshlrev_b32_e32 v18, 16, v10
	v_lshlrev_b32_e32 v20, 16, v11
	v_and_b32_e32 v23, 0xffff0000, v12
	v_and_b32_e32 v27, 0xffff0000, v13
	v_mul_f32_e32 v9, v9, v9
	v_mul_f32_e32 v17, v17, v17
	v_mul_f32_e32 v19, v19, v19
	v_mul_f32_e32 v21, v21, v21
	v_lshlrev_b32_e32 v22, 16, v12
	v_lshlrev_b32_e32 v26, 16, v13
	v_and_b32_e32 v29, 0xffff0000, v14
	v_and_b32_e32 v31, 0xffff0000, v15
	v_mul_f32_e32 v23, v23, v23
	v_mul_f32_e32 v27, v27, v27
	v_fmac_f32_e32 v9, v8, v8
	v_fmac_f32_e32 v17, v16, v16
	v_fmac_f32_e32 v19, v18, v18
	v_fmac_f32_e32 v21, v20, v20
	v_lshlrev_b32_e32 v28, 16, v14
	v_lshlrev_b32_e32 v30, 16, v15
	v_mul_f32_e32 v29, v29, v29
	v_mul_f32_e32 v31, v31, v31
	v_fmac_f32_e32 v23, v22, v22
	v_fmac_f32_e32 v27, v26, v26
	v_add_f32_e32 v8, v9, v17
	v_add_f32_e32 v9, v19, v21
	v_fmac_f32_e32 v29, v28, v28
	v_fmac_f32_e32 v31, v30, v30
	v_add_f32_e32 v16, v23, v27
	v_add_f32_e32 v8, v8, v9
	v_add_f32_e32 v8, v8, v16
	v_add_f32_e32 v9, v29, v31
	v_add_f32_e32 v8, v8, v9
	ds_bpermute_b32 v9, v0, v8
	global_store_dwordx2 v7, v[24:25], s[6:7] sc0 sc1
	global_store_dwordx2 v7, v[10:11], s[6:7] offset:512 sc0 sc1
	global_store_dwordx2 v7, v[12:13], s[6:7] offset:1024 sc0 sc1
	global_store_dwordx2 v7, v[14:15], s[6:7] offset:1536 sc0 sc1
	s_waitcnt lgkmcnt(0)
	v_add_f32_e32 v8, v8, v9
	ds_bpermute_b32 v9, v1, v8
	s_waitcnt lgkmcnt(0)
	v_add_f32_e32 v8, v8, v9
	ds_bpermute_b32 v9, v2, v8
	s_waitcnt lgkmcnt(0)
	v_add_f32_e32 v8, v8, v9
	ds_bpermute_b32 v9, v3, v8
	s_waitcnt lgkmcnt(0)
	v_add_f32_e32 v8, v8, v9
	ds_bpermute_b32 v9, v4, v8
	s_waitcnt lgkmcnt(0)
	v_add_f32_e32 v8, v8, v9
	ds_bpermute_b32 v9, v5, v8
	s_and_saveexec_b64 s[10:11], vcc
	s_cbranch_execz .LBB0_14
	s_waitcnt lgkmcnt(0)
	v_add_f32_e32 v8, v8, v9
	v_fma_f32 v8, v8, s80, 0.5
	v_trunc_f32_e32 v8, v8
	v_mul_f32_e32 v9, 0x2f800000, v8
	v_floor_f32_e32 v9, v9
	v_fmac_f32_e32 v8, 0xcf800000, v9
	v_cvt_u32_f32_e32 v8, v8
	v_cvt_u32_f32_e32 v9, v9
	global_store_dwordx2 v195, v[8:9], s[8:9]
	s_branch .LBB0_14

; DI void unpack8(const u32x4 w, float* x) { x[0] = bflo(w.x); x[1] = bfhi(w.x); x[2] = bflo(w.y); x[3] = bfhi(w.y); x[4] = bflo(w.z); x[5] = bfhi(w.z); x[6] = bflo(w.w); x[7] = bfhi(w.w); }
; DI u32x4 pack8(const float* x) { u32x4 w; w.x = pk2(x[0], x[1]); w.y = pk2(x[2], x[3]); w.z = pk2(x[4], x[5]); w.w = pk2(x[6], x[7]); return w; }
; DI void merge_a(const bf16_t* QKV, const float* LSE, bf16_t* AO, int gtid, int gthreads) {
;     for (int idx = gtid; idx < TC * 64; idx += gthreads) {
;         const int j = idx & 7, h = (idx >> 3) & 7, row = idx >> 6;
;         const __attribute__((address_space(1))) float* LSEg = (const __attribute__((address_space(1))) float*)LSE; const float l0 = LSEg[((size_t)0 * TC + row) * 8 + h], l1 = LSEg[((size_t)1 * TC + row) * 8 + h], l2 = LSEg[((size_t)2 * TC + row) * 8 + h];
;         const float m = fmaxf(l0, fmaxf(l1, l2));
;         float w0 = __builtin_amdgcn_exp2f(l0 - m), w1 = __builtin_amdgcn_exp2f(l1 - m), w2 = __builtin_amdgcn_exp2f(l2 - m);
;         const float inv = 1.0f / (w0 + w1 + w2); w0 *= inv; w1 *= inv; w2 *= inv;
;         const __attribute__((address_space(1))) bf16_t* p = (const __attribute__((address_space(1))) bf16_t*)QKV + (size_t)row * 4608 + h * 64 + j * 8;
;         float a[8], b[8], cc[8], y[8]; unpack8(*(const __attribute__((address_space(1))) u32x4*)p, a); unpack8(*(const __attribute__((address_space(1))) u32x4*)(p + 1536), b); unpack8(*(const __attribute__((address_space(1))) u32x4*)(p + 3072), cc);
; #pragma unroll
;         for (int e = 0; e < 8; ++e) y[e] = w0 * a[e] + w1 * b[e] + w2 * cc[e];
;         *(__attribute__((address_space(1))) u32x4*)((__attribute__((address_space(1))) bf16_t*)AO + (size_t)row * 512 + h * 64 + j * 8) = pack8(y);
;     }
.LBB0_118:
	v_ashrrev_i32_e32 v14, 6, v1
	v_and_b32_e32 v4, 56, v0
	v_ashrrev_i32_e32 v15, 31, v14
	v_bfe_u32 v8, v1, 3, 3
	v_lshlrev_b32_e32 v16, 1, v4
	v_lshlrev_b64 v[4:5], 5, v[14:15]
	v_mov_b64_e32 v[2:3], s[70:71]
	v_lshlrev_b32_e32 v194, 2, v8
	s_movk_i32 s12, 0x2400
	v_lshl_add_u64 v[4:5], s[30:31], 0, v[4:5]
	v_mad_i64_i32 v[2:3], s[12:13], v14, s12, v[2:3]
	v_lshl_add_u64 v[6:7], v[4:5], 0, v[194:195]
	v_lshlrev_b32_e32 v194, 7, v8
	v_mov_b32_e32 v17, v195
	v_add_co_u32_e32 v8, vcc, 0x80000, v6
	v_lshl_add_u64 v[2:3], v[2:3], 0, v[194:195]
	s_waitcnt lgkmcnt(0)
	v_addc_co_u32_e32 v9, vcc, 0, v7, vcc
	v_lshl_add_u64 v[10:11], v[2:3], 0, v[16:17]
	global_load_dword v32, v[6:7], off
	global_load_dwordx4 v[2:5], v[10:11], off offset:3072
	v_add_co_u32_e32 v6, vcc, s17, v6
	v_lshlrev_b64 v[14:15], 10, v[14:15]
	s_nop 0
	v_addc_co_u32_e32 v7, vcc, 0, v7, vcc
	v_add_co_u32_e32 v12, vcc, s16, v10
	v_lshl_add_u64 v[14:15], s[72:73], 0, v[14:15]
	s_nop 0
	v_addc_co_u32_e32 v13, vcc, 0, v11, vcc
	global_load_dword v33, v[8:9], off
	global_load_dword v34, v[6:7], off
	s_nop 0
	global_load_dwordx4 v[6:9], v[10:11], off
	s_nop 0
	global_load_dwordx4 v[10:13], v[12:13], off offset:2048
	v_lshl_add_u64 v[14:15], v[14:15], 0, v[194:195]
	v_lshl_add_u64 v[14:15], v[14:15], 0, v[16:17]
	v_add_u32_e32 v1, s64, v1
	s_mov_b32 s12, 0xfffff
	v_cmp_lt_i32_e32 vcc, s12, v1
	s_or_b64 s[22:23], vcc, s[22:23]
	v_add_u32_e32 v0, s66, v0
	s_waitcnt vmcnt(0)
	v_lshlrev_b32_e32 v24, 16, v4
	v_and_b32_e32 v27, 0xffff0000, v4
	v_lshlrev_b32_e32 v18, 16, v2
	v_and_b32_e32 v21, 0xffff0000, v2
	v_lshlrev_b32_e32 v2, 16, v3
	v_and_b32_e32 v23, 0xffff0000, v3
	v_lshlrev_b32_e32 v16, 16, v5
	v_and_b32_e32 v5, 0xffff0000, v5
	s_waitcnt vmcnt(2)
	v_max3_f32 v35, v32, v33, v34
	s_waitcnt vmcnt(1)
	v_and_b32_e32 v17, 0xffff0000, v9
	v_lshlrev_b32_e32 v4, 16, v9
	s_waitcnt vmcnt(0)
	v_lshlrev_b32_e32 v30, 16, v10
	v_and_b32_e32 v31, 0xffff0000, v10
	v_and_b32_e32 v25, 0xffff0000, v8
	v_lshlrev_b32_e32 v26, 16, v8
	v_lshlrev_b32_e32 v8, 16, v12
	v_and_b32_e32 v9, 0xffff0000, v12
	v_sub_f32_e32 v10, v32, v35
	v_sub_f32_e32 v12, v33, v35
	v_lshlrev_b32_e32 v28, 16, v13
	v_and_b32_e32 v29, 0xffff0000, v13
	v_and_b32_e32 v19, 0xffff0000, v6
	v_lshlrev_b32_e32 v20, 16, v6
	v_and_b32_e32 v3, 0xffff0000, v7
	v_lshlrev_b32_e32 v22, 16, v7
	v_lshlrev_b32_e32 v6, 16, v11
	v_and_b32_e32 v7, 0xffff0000, v11
	v_sub_f32_e32 v13, v34, v35
	v_exp_f32_e32 v11, v10
	v_exp_f32_e32 v10, v12
	v_exp_f32_e32 v13, v13
	v_add_f32_e32 v12, v11, v10
	v_add_f32_e32 v12, v13, v12
	v_div_scale_f32 v32, s[12:13], v12, v12, 1.0
	v_rcp_f32_e32 v34, v32
	v_div_scale_f32 v33, vcc, 1.0, v12, 1.0
	v_fma_f32 v35, -v32, v34, 1.0
	v_fmac_f32_e32 v34, v35, v34
	v_mul_f32_e32 v35, v33, v34
	v_fma_f32 v36, -v32, v35, v33
	v_fmac_f32_e32 v35, v36, v34
	v_fma_f32 v32, -v32, v35, v33
	v_div_fmas_f32 v32, v32, v34, v35
	v_div_fixup_f32 v12, v32, v12, 1.0
	v_pk_mul_f32 v[10:11], v[10:11], v[12:13] op_sel_hi:[1,0]
	v_mul_f32_e32 v32, v13, v12
	v_pk_mul_f32 v[12:13], v[10:11], v[20:21] op_sel:[1,0] op_sel_hi:[0,1]
	v_pk_mul_f32 v[20:21], v[10:11], v[22:23] op_sel:[1,0] op_sel_hi:[0,1]
	v_pk_mul_f32 v[22:23], v[10:11], v[26:27] op_sel:[1,0] op_sel_hi:[0,1]
	v_pk_mul_f32 v[4:5], v[10:11], v[4:5] op_sel:[1,0] op_sel_hi:[0,1]
	v_pk_fma_f32 v[12:13], v[10:11], v[18:19], v[12:13]
	v_pk_fma_f32 v[2:3], v[10:11], v[2:3], v[20:21]
	v_pk_fma_f32 v[18:19], v[10:11], v[24:25], v[22:23]
	v_pk_fma_f32 v[4:5], v[10:11], v[16:17], v[4:5]
	v_pk_fma_f32 v[10:11], v[32:33], v[30:31], v[12:13] op_sel_hi:[0,1,1]
	v_pk_fma_f32 v[6:7], v[32:33], v[6:7], v[2:3] op_sel_hi:[0,1,1]
	v_pk_fma_f32 v[8:9], v[32:33], v[8:9], v[18:19] op_sel_hi:[0,1,1]
	v_pk_fma_f32 v[12:13], v[32:33], v[28:29], v[4:5] op_sel_hi:[0,1,1]
	v_cvt_pk_bf16_f32 v2, v10, v11
	v_cvt_pk_bf16_f32 v3, v6, v7
	v_cvt_pk_bf16_f32 v4, v8, v9
	v_cvt_pk_bf16_f32 v5, v12, v13
	global_store_dwordx4 v[14:15], v[2:5], off sc0 sc1
	s_andn2_b64 exec, exec, s[22:23]
	s_cbranch_execnz .LBB0_118

; DI u32x4 pack8(const float* x) { u32x4 w; w.x = pk2(x[0], x[1]); w.y = pk2(x[2], x[3]); w.z = pk2(x[4], x[5]); w.w = pk2(x[6], x[7]); return w; }
; DI void prep_d1(const bf16_t* cmb, bf16_t* cqn, bf16_t* ckvn, bf16_t* kr, const float* qg, const float* kvg, int seq_len, const f32x2* tabD, int gw, int ngw, int lane) {
;     ...
;         float sa = 0.f, sb = 0.f;
; #pragma unroll
;         for (int e = 0; e < 8; ++e) { sa += xa[e] * xa[e]; sb += xb[e] * xb[e]; }
;         const float sq = wave_sum(lane < 48 ? sa : 0.f), skv = wave_sum((lane >= 48 ? sa : 0.f) + (lane < 16 ? sb : 0.f));
;         const float rq = 1.0f / sqrtf(sq * (1.f / 384.f) + NORM_EPS), rkv = 1.0f / sqrtf(skv * (1.f / 256.f) + NORM_EPS);
;         float y[8];
;         if (lane < 48) {
; #pragma unroll
;             for (int e = 0; e < 8; ++e) y[e] = xa[e] * rq * qg[8 * lane + e];
;             *(__attribute__((address_space(1))) u32x4*)((__attribute__((address_space(1))) bf16_t*)cqn + (size_t)row * 384 + 8 * lane) = pack8(y);
;         } else {
; #pragma unroll
;             for (int e = 0; e < 8; ++e) y[e] = xa[e] * rkv * kvg[8 * (lane - 48) + e];
;             *(__attribute__((address_space(1))) u32x4*)((__attribute__((address_space(1))) bf16_t*)ckvn + (size_t)row * 256 + 8 * (lane - 48)) = pack8(y);
;         }
;         if (lane < 16) {
; #pragma unroll
;             for (int e = 0; e < 8; ++e) y[e] = xb[e] * rkv * kvg[128 + 8 * lane + e];
;             *(__attribute__((address_space(1))) u32x4*)((__attribute__((address_space(1))) bf16_t*)ckvn + (size_t)row * 256 + 128 + 8 * lane) = pack8(y);
;         }
;         const int pos = row % seq_len; const int jj = (lane - 16) & 3; const bool first = jj < 2;
;         const f32x2* tb = tabD + (size_t)pos * 16 + 8 * (jj & 1);
; #pragma unroll
;         for (int e = 0; e < 8; ++e) { const float other = __shfl_xor(xb[e], 2); const f32x2 cs = tb[e]; y[e] = first ? xb[e] * cs.x - other * cs.y : xb[e] * cs.x + other * cs.y; }
;         if (lane >= 16 && lane < 20) *(__attribute__((address_space(1))) u32x4*)((__attribute__((address_space(1))) bf16_t*)kr + (size_t)row * 32 + 8 * jj) = pack8(y);
.LBB0_307:
	s_waitcnt lgkmcnt(0)
	global_load_dwordx4 v[0:3], v[6:7], off offset:528
	global_load_dwordx4 v[30:33], v[6:7], off offset:512
	v_pk_mul_f32 v[26:27], v[24:25], v[28:29] op_sel_hi:[1,0]
	s_waitcnt vmcnt(0)
	v_pk_mul_f32 v[26:27], v[26:27], v[30:31]
	v_pk_mul_f32 v[30:31], v[22:23], v[28:29] op_sel_hi:[1,0]
	s_nop 0
	v_pk_mul_f32 v[30:31], v[30:31], v[32:33]
	v_pk_mul_f32 v[32:33], v[20:21], v[28:29] op_sel_hi:[1,0]
	s_nop 0
	v_pk_mul_f32 v[32:33], v[32:33], v[0:1]
	v_pk_mul_f32 v[0:1], v[18:19], v[28:29] op_sel_hi:[1,0]
	s_nop 0
	v_pk_mul_f32 v[28:29], v[0:1], v[2:3]
	v_cvt_pk_bf16_f32 v0, v26, v27
	v_cvt_pk_bf16_f32 v1, v30, v31
	v_cvt_pk_bf16_f32 v2, v32, v33
	v_cvt_pk_bf16_f32 v3, v28, v29
	global_store_dwordx4 v[12:13], v[0:3], off sc0 sc1
.LBB0_308:
	s_or_b64 exec, exec, s[30:31]
	ds_bpermute_b32 v28, v38, v24
	ds_bpermute_b32 v29, v38, v25
	ds_bpermute_b32 v26, v38, v22
	ds_bpermute_b32 v27, v38, v23
	ds_bpermute_b32 v2, v38, v20
	ds_bpermute_b32 v3, v38, v21
	ds_bpermute_b32 v0, v38, v18
	s_waitcnt lgkmcnt(7)
	ds_bpermute_b32 v1, v38, v19
	s_and_saveexec_b64 s[30:31], s[52:53]
	s_cbranch_execz .LBB0_301
	s_abs_i32 s13, s22
	s_mul_hi_u32 s16, s13, s91
	v_readlane_b32 s17, v254, 29
	s_mul_i32 s16, s16, s17
	s_sub_i32 s13, s13, s16
	s_ashr_i32 s12, s22, 31
	s_sub_i32 s16, s13, s17
	s_cmp_ge_u32 s13, s17
	s_cselect_b32 s13, s16, s13
	s_sub_i32 s16, s13, s17
	s_cmp_ge_u32 s13, s17
	s_cselect_b32 s13, s16, s13
	s_xor_b32 s13, s13, s12
	s_sub_i32 s12, s13, s12
	s_ashr_i32 s13, s12, 31
	s_lshl_b64 s[12:13], s[12:13], 7
	v_lshl_add_u64 v[36:37], v[4:5], 0, s[12:13]
	flat_load_dwordx4 v[30:33], v[36:37]
	s_waitcnt vmcnt(0) lgkmcnt(0)
	v_mov_b32_e32 v45, v32
	v_mov_b32_e32 v32, v31
	v_pk_mul_f32 v[28:29], v[32:33], v[28:29]
	v_mov_b32_e32 v44, v30
	v_cndmask_b32_e64 v29, v29, -v29, s[50:51]
	v_cndmask_b32_e64 v28, v28, -v28, s[50:51]
	v_pk_fma_f32 v[32:33], v[24:25], v[44:45], v[28:29]
	flat_load_dwordx4 v[28:31], v[36:37] offset:16
	s_waitcnt vmcnt(0) lgkmcnt(0)
	v_mov_b32_e32 v25, v30
	v_mov_b32_e32 v30, v29
	v_pk_mul_f32 v[26:27], v[30:31], v[26:27]
	v_mov_b32_e32 v24, v28
	v_cndmask_b32_e64 v27, v27, -v27, s[50:51]
	v_cndmask_b32_e64 v26, v26, -v26, s[50:51]
	v_pk_fma_f32 v[26:27], v[22:23], v[24:25], v[26:27]
	flat_load_dwordx4 v[22:25], v[36:37] offset:32
	s_waitcnt vmcnt(0) lgkmcnt(0)
	v_mov_b32_e32 v29, v24
	v_mov_b32_e32 v24, v23
	v_pk_mul_f32 v[2:3], v[24:25], v[2:3]
	v_mov_b32_e32 v28, v22
	v_cndmask_b32_e64 v3, v3, -v3, s[50:51]
	v_cndmask_b32_e64 v2, v2, -v2, s[50:51]
	v_pk_fma_f32 v[2:3], v[20:21], v[28:29], v[2:3]
	flat_load_dwordx4 v[20:23], v[36:37] offset:48
	v_cvt_pk_bf16_f32 v2, v2, v3
	s_waitcnt vmcnt(0) lgkmcnt(0)
	v_mov_b32_e32 v25, v22
	v_mov_b32_e32 v22, v21
	v_pk_mul_f32 v[0:1], v[22:23], v[0:1]
	v_mov_b32_e32 v24, v20
	v_cndmask_b32_e64 v1, v1, -v1, s[50:51]
	v_cndmask_b32_e64 v0, v0, -v0, s[50:51]
	v_pk_fma_f32 v[18:19], v[18:19], v[24:25], v[0:1]
	v_cvt_pk_bf16_f32 v0, v32, v33
	v_cvt_pk_bf16_f32 v1, v26, v27
	v_cvt_pk_bf16_f32 v3, v18, v19
	global_store_dwordx4 v[14:15], v[0:3], off sc0 sc1
	s_branch .LBB0_301
.LBB0_310:
	s_waitcnt lgkmcnt(0)
	global_load_dwordx4 v[0:3], v[6:7], off offset:-1536
	global_load_dwordx4 v[44:47], v[6:7], off offset:-1520
	v_pk_mul_f32 v[36:37], v[28:29], v[36:37] op_sel_hi:[0,1]
	v_pk_mul_f32 v[32:33], v[28:29], v[32:33] op_sel_hi:[0,1]
	v_pk_mul_f32 v[30:31], v[28:29], v[30:31] op_sel_hi:[0,1]
	v_pk_mul_f32 v[26:27], v[28:29], v[26:27] op_sel_hi:[0,1]
	s_waitcnt vmcnt(1)
	v_pk_mul_f32 v[0:1], v[36:37], v[0:1]
	v_pk_mul_f32 v[2:3], v[32:33], v[2:3]
	s_waitcnt vmcnt(0)
	v_pk_mul_f32 v[30:31], v[30:31], v[44:45]
	v_pk_mul_f32 v[26:27], v[26:27], v[46:47]
	v_cvt_pk_bf16_f32 v0, v0, v1
	v_cvt_pk_bf16_f32 v1, v2, v3
	v_cvt_pk_bf16_f32 v2, v30, v31
	v_cvt_pk_bf16_f32 v3, v26, v27
	global_store_dwordx4 v[12:13], v[0:3], off offset:-1024 sc0 sc1
	s_andn2_saveexec_b64 s[30:31], s[30:31]
	s_cbranch_execz .LBB0_306
.LBB0_311:
	s_waitcnt lgkmcnt(0)
	v_add_f32_e32 v0, v0, v1
	v_fmamk_f32 v0, v0, 0x3b2aaaab, v237
	v_cmp_gt_f32_e32 vcc, s68, v0
	v_mul_f32_e32 v1, 0x4f800000, v0
	s_nop 0
	v_cndmask_b32_e32 v0, v0, v1, vcc
	v_sqrt_f32_e32 v1, v0
	s_nop 0
	v_add_u32_e32 v2, -1, v1
	v_fma_f32 v3, -v2, v1, v0
	v_cmp_ge_f32_e64 s[56:57], 0, v3
	v_add_u32_e32 v3, 1, v1
	s_nop 0
	v_cndmask_b32_e64 v2, v1, v2, s[56:57]
	v_fma_f32 v1, -v3, v1, v0
	v_cmp_lt_f32_e64 s[56:57], 0, v1
	s_nop 1
	v_cndmask_b32_e64 v1, v2, v3, s[56:57]
	v_mul_f32_e32 v2, 0x37800000, v1
	v_cndmask_b32_e32 v1, v1, v2, vcc
	v_cmp_class_f32_e32 vcc, v0, v238
	s_nop 1
	v_cndmask_b32_e32 v0, v1, v0, vcc
	v_div_scale_f32 v1, s[12:13], v0, v0, 1.0
	v_rcp_f32_e32 v2, v1
	s_nop 0
	v_fma_f32 v3, -v1, v2, 1.0
	v_fmac_f32_e32 v2, v3, v2
	v_div_scale_f32 v3, vcc, 1.0, v0, 1.0
	v_mul_f32_e32 v29, v3, v2
	v_fma_f32 v34, -v1, v29, v3
	v_fmac_f32_e32 v29, v34, v2
	v_fma_f32 v1, -v1, v29, v3
	v_div_fmas_f32 v1, v1, v2, v29
	v_div_fixup_f32 v34, v1, v0, 1.0
	global_load_dwordx4 v[0:3], v[8:9], off offset:16
	global_load_dwordx4 v[44:47], v[8:9], off
	v_pk_mul_f32 v[30:31], v[34:35], v[30:31] op_sel_hi:[0,1]
	v_pk_mul_f32 v[36:37], v[34:35], v[36:37] op_sel_hi:[0,1]
	v_pk_mul_f32 v[32:33], v[34:35], v[32:33] op_sel_hi:[0,1]
	s_waitcnt vmcnt(1)
	v_pk_mul_f32 v[30:31], v[30:31], v[0:1]
	v_pk_mul_f32 v[0:1], v[34:35], v[26:27] op_sel_hi:[0,1]
	s_waitcnt vmcnt(0)
	v_pk_mul_f32 v[36:37], v[36:37], v[44:45]
	v_pk_mul_f32 v[32:33], v[32:33], v[46:47]
	v_pk_mul_f32 v[26:27], v[0:1], v[2:3]
	v_cvt_pk_bf16_f32 v0, v36, v37
	v_cvt_pk_bf16_f32 v1, v32, v33
	v_cvt_pk_bf16_f32 v2, v30, v31
	v_cvt_pk_bf16_f32 v3, v26, v27
	global_store_dwordx4 v[10:11], v[0:3], off sc0 sc1
	s_or_b64 exec, exec, s[30:31]
	s_and_saveexec_b64 s[30:31], s[48:49]
	s_cbranch_execnz .LBB0_307
	s_branch .LBB0_308

; DI void unpack8(const u32x4 w, float* x) { x[0] = bflo(w.x); x[1] = bfhi(w.x); x[2] = bflo(w.y); x[3] = bfhi(w.y); x[4] = bflo(w.z); x[5] = bfhi(w.z); x[6] = bflo(w.w); x[7] = bfhi(w.w); }
; DI u32x4 pack8(const float* x) { u32x4 w; w.x = pk2(x[0], x[1]); w.y = pk2(x[2], x[3]); w.z = pk2(x[4], x[5]); w.w = pk2(x[6], x[7]); return w; }
; DI void prep_b(bf16_t* X, const float* qg, const float* kg, int seq_len, const f32x2* tabB, int gtid, int gthreads) {
;     const int total = TC * 20 * 8;
;     for (int idx = gtid; idx < total; idx += gthreads) {
;         const int j = idx & 7, vi = idx >> 3; const int row = vi / 20, vv = vi - row * 20;
;         bf16_t* p = X + (size_t)row * 1536 + (vv < 16 ? vv * 64 : 1024 + (vv - 16) * 64) + j * 8;
;         const __attribute__((address_space(1))) float* g = (const __attribute__((address_space(1))) float*)(vv < 16 ? qg : kg) + j * 8;
;         float x[8]; unpack8(*(const __attribute__((address_space(1))) u32x4*)p, x);
;         float ss = 0.f;
; #pragma unroll
;         for (int e = 0; e < 8; ++e) ss += x[e] * x[e];
;         ss += __shfl_xor(ss, 1); ss += __shfl_xor(ss, 2); ss += __shfl_xor(ss, 4);
;         const float rstd = 1.0f / sqrtf(ss * (1.f / 64.f) + NORM_EPS);
;         const int t = row % seq_len; const int pos = (j >> 2) ? (t & 63) : (t >> 6); const int jj = j & 3; const bool first = jj < 2;
;         const __attribute__((address_space(1))) f32x2* tb = (const __attribute__((address_space(1))) f32x2*)tabB + pos * 16 + 8 * (jj & 1);
;         float y[8];
; #pragma unroll
;         for (int e = 0; e < 8; ++e) { x[e] = x[e] * rstd * g[e] * (vv < 16 ? 0.125f * LOG2E : 1.0f); }
; #pragma unroll
;         for (int e = 0; e < 8; ++e) { const float other = __shfl_xor(x[e], 2); const f32x2 cs = tb[e]; y[e] = first ? x[e] * cs.x - other * cs.y : x[e] * cs.x + other * cs.y; }
;         *(__attribute__((address_space(1))) u32x4*)p = pack8(y);
;     }
.LBB0_318:
	v_ashrrev_i32_e32 v2, 3, v31
	s_mov_b32 s12, 0x66666667
	v_mul_hi_i32 v3, v2, s12
	v_and_b32_e32 v50, 2, v31
	v_add_u32_e32 v31, s64, v31
	s_mov_b32 s12, 0x27ffff
	v_lshrrev_b32_e32 v9, 31, v3
	v_ashrrev_i32_e32 v3, 3, v3
	v_cmp_lt_i32_e32 vcc, s12, v31
	v_add_u32_e32 v12, v3, v9
	s_movk_i32 s12, 0xffec
	v_mad_u64_u32 v[2:3], s[12:13], v12, s12, v[2:3]
	v_mov_b64_e32 v[4:5], s[70:71]
	v_mov_b32_e32 v6, s19
	v_mov_b32_e32 v7, s17
	s_or_b64 s[42:43], vcc, s[42:43]
	v_sub_u32_e32 v3, 0, v12
	v_cmp_gt_i32_e32 vcc, 16, v2
	v_lshlrev_b32_e32 v2, 6, v2
	v_mad_i64_i32 v[4:5], s[12:13], v12, s95, v[4:5]
	v_cndmask_b32_e32 v9, v6, v7, vcc
	v_max_i32_e32 v6, v12, v3
	v_ashrrev_i32_e32 v3, 31, v2
	v_lshlrev_b32_e32 v194, 1, v0
	v_mul_hi_u32 v7, v6, s91
	v_lshl_add_u64 v[2:3], v[2:3], 1, v[4:5]
	v_mov_b32_e32 v8, s18
	v_mov_b32_e32 v10, s16
	v_mul_lo_u32 v4, v7, s24
	v_lshl_add_u64 v[2:3], v[2:3], 0, v[194:195]
	v_cndmask_b32_e32 v8, v8, v10, vcc
	v_sub_u32_e32 v10, v6, v4
	global_load_dwordx4 v[4:7], v[2:3], off
	v_ashrrev_i32_e32 v20, 31, v12
	v_cndmask_b32_e32 v24, 1.0, v248, vcc
	v_lshlrev_b32_e32 v194, 2, v0
	v_subrev_u32_e32 v12, s24, v10
	v_cmp_le_u32_e32 vcc, s24, v10
	v_lshl_add_u64 v[8:9], v[8:9], 0, v[194:195]
	v_and_b32_e32 v11, 8, v30
	v_cndmask_b32_e32 v10, v10, v12, vcc
	global_load_dwordx4 v[12:15], v[8:9], off offset:16
	global_load_dwordx4 v[16:19], v[8:9], off
	v_subrev_u32_e32 v8, s24, v10
	v_cmp_le_u32_e32 vcc, s24, v10
	v_lshlrev_b32_e32 v194, 3, v11
	v_add_u32_e32 v30, s66, v30
	v_cndmask_b32_e32 v8, v10, v8, vcc
	v_xor_b32_e32 v8, v8, v20
	v_sub_u32_e32 v8, v8, v20
	v_and_b32_e32 v9, 63, v8
	v_ashrrev_i32_e32 v8, 6, v8
	v_cndmask_b32_e64 v8, v9, v8, s[0:1]
	v_lshlrev_b32_e32 v8, 4, v8
	v_ashrrev_i32_e32 v9, 31, v8
	v_lshl_add_u64 v[8:9], v[8:9], 3, s[36:37]
	v_lshl_add_u64 v[8:9], v[8:9], 0, v[194:195]
	global_load_dwordx4 v[20:23], v[8:9], off
	global_load_dwordx4 v[32:35], v[8:9], off offset:16
	global_load_dwordx4 v[36:39], v[8:9], off offset:32
	global_load_dwordx4 v[40:43], v[8:9], off offset:48
	s_waitcnt vmcnt(0)
	v_lshlrev_b32_e32 v48, 16, v4
	v_and_b32_e32 v49, 0xffff0000, v4
	v_lshlrev_b32_e32 v46, 16, v5
	v_and_b32_e32 v47, 0xffff0000, v5
	v_pk_mul_f32 v[10:11], v[48:49], v[48:49]
	v_pk_mul_f32 v[8:9], v[46:47], v[46:47]
	v_add_f32_e32 v10, v10, v11
	v_lshlrev_b32_e32 v44, 16, v6
	v_and_b32_e32 v45, 0xffff0000, v6
	v_add_f32_e32 v8, v8, v10
	v_lshlrev_b32_e32 v26, 16, v7
	v_and_b32_e32 v27, 0xffff0000, v7
	v_pk_mul_f32 v[6:7], v[44:45], v[44:45]
	v_add_f32_e32 v8, v9, v8
	v_add_f32_e32 v6, v6, v8
	v_pk_mul_f32 v[4:5], v[26:27], v[26:27]
	v_add_f32_e32 v6, v7, v6
	v_add_f32_e32 v4, v4, v6
	v_add_f32_e32 v25, v5, v4
	ds_bpermute_b32 v51, v1, v25
	s_waitcnt vmcnt(3)
	v_mov_b32_e32 v4, v20
	v_mov_b32_e32 v5, v22
	v_mov_b32_e32 v22, v21
	s_waitcnt lgkmcnt(0)
	v_add_f32_e32 v20, v25, v51
	ds_bpermute_b32 v21, v28, v20
	s_waitcnt vmcnt(2)
	v_mov_b32_e32 v6, v32
	v_mov_b32_e32 v7, v34
	v_mov_b32_e32 v34, v33
	s_waitcnt vmcnt(1)
	v_mov_b32_e32 v8, v36
	s_waitcnt lgkmcnt(0)
	v_add_f32_e32 v20, v20, v21
	ds_bpermute_b32 v21, v29, v20
	v_mov_b32_e32 v9, v38
	v_mov_b32_e32 v38, v37
	s_waitcnt vmcnt(0)
	v_mov_b32_e32 v10, v40
	v_mov_b32_e32 v11, v42
	s_waitcnt lgkmcnt(0)
	v_add_f32_e32 v20, v20, v21
	v_fmamk_f32 v20, v20, 0x3c800000, v237
	v_mul_f32_e32 v21, 0x4f800000, v20
	v_cmp_gt_f32_e32 vcc, s68, v20
	v_mov_b32_e32 v42, v41
	s_nop 0
	v_cndmask_b32_e32 v20, v20, v21, vcc
	v_sqrt_f32_e32 v21, v20
	s_nop 0
	v_add_u32_e32 v25, -1, v21
	v_add_u32_e32 v32, 1, v21
	v_fma_f32 v33, -v25, v21, v20
	v_fma_f32 v36, -v32, v21, v20
	v_cmp_ge_f32_e64 s[44:45], 0, v33
	s_nop 1
	v_cndmask_b32_e64 v21, v21, v25, s[44:45]
	v_cmp_lt_f32_e64 s[44:45], 0, v36
	s_nop 1
	v_cndmask_b32_e64 v21, v21, v32, s[44:45]
	v_mul_f32_e32 v25, 0x37800000, v21
	v_cndmask_b32_e32 v21, v21, v25, vcc
	v_cmp_class_f32_e32 vcc, v20, v238
	s_nop 1
	v_cndmask_b32_e32 v20, v21, v20, vcc
	v_div_scale_f32 v21, s[12:13], v20, v20, 1.0
	v_rcp_f32_e32 v32, v21
	v_div_scale_f32 v25, vcc, 1.0, v20, 1.0
	v_fma_f32 v33, -v21, v32, 1.0
	v_fmac_f32_e32 v32, v33, v32
	v_mul_f32_e32 v33, v25, v32
	v_fma_f32 v36, -v21, v33, v25
	v_fmac_f32_e32 v33, v36, v32
	v_fma_f32 v21, -v21, v33, v25
	v_div_fmas_f32 v21, v21, v32, v33
	v_div_fixup_f32 v20, v21, v20, 1.0
	v_pk_mul_f32 v[32:33], v[20:21], v[48:49] op_sel_hi:[0,1]
	v_pk_mul_f32 v[36:37], v[20:21], v[46:47] op_sel_hi:[0,1]
	v_pk_mul_f32 v[40:41], v[20:21], v[44:45] op_sel_hi:[0,1]
	v_pk_mul_f32 v[20:21], v[20:21], v[26:27] op_sel_hi:[0,1]
	v_pk_mul_f32 v[16:17], v[16:17], v[32:33]
	v_pk_mul_f32 v[18:19], v[18:19], v[36:37]
	v_pk_mul_f32 v[26:27], v[12:13], v[40:41]
	v_pk_mul_f32 v[20:21], v[14:15], v[20:21]
	v_pk_mul_f32 v[12:13], v[24:25], v[16:17] op_sel_hi:[0,1]
	v_pk_mul_f32 v[14:15], v[24:25], v[18:19] op_sel_hi:[0,1]
	v_pk_mul_f32 v[16:17], v[24:25], v[26:27] op_sel_hi:[0,1]
	v_pk_mul_f32 v[18:19], v[24:25], v[20:21] op_sel_hi:[0,1]
	ds_bpermute_b32 v20, v28, v12
	ds_bpermute_b32 v21, v28, v13
	ds_bpermute_b32 v24, v28, v14
	ds_bpermute_b32 v25, v28, v15
	ds_bpermute_b32 v32, v28, v16
	ds_bpermute_b32 v33, v28, v17
	ds_bpermute_b32 v36, v28, v18
	ds_bpermute_b32 v37, v28, v19
	s_waitcnt lgkmcnt(6)
	v_pk_mul_f32 v[26:27], v[22:23], v[20:21]
	s_waitcnt lgkmcnt(4)
	v_pk_mul_f32 v[24:25], v[34:35], v[24:25]
	s_waitcnt lgkmcnt(2)
	v_pk_mul_f32 v[22:23], v[38:39], v[32:33]
	v_cmp_eq_u32_e32 vcc, 0, v50
	s_waitcnt lgkmcnt(0)
	v_pk_mul_f32 v[20:21], v[42:43], v[36:37]
	v_cndmask_b32_e64 v27, v27, -v27, vcc
	v_cndmask_b32_e64 v26, v26, -v26, vcc
	v_cndmask_b32_e64 v25, v25, -v25, vcc
	v_cndmask_b32_e64 v24, v24, -v24, vcc
	v_cndmask_b32_e64 v23, v23, -v23, vcc
	v_cndmask_b32_e64 v22, v22, -v22, vcc
	v_cndmask_b32_e64 v21, v21, -v21, vcc
	v_cndmask_b32_e64 v20, v20, -v20, vcc
	v_pk_fma_f32 v[4:5], v[4:5], v[12:13], v[26:27]
	v_pk_fma_f32 v[6:7], v[6:7], v[14:15], v[24:25]
	v_pk_fma_f32 v[8:9], v[16:17], v[8:9], v[22:23]
	v_pk_fma_f32 v[10:11], v[18:19], v[10:11], v[20:21]
	v_cvt_pk_bf16_f32 v4, v4, v5
	v_cvt_pk_bf16_f32 v5, v6, v7
	v_cvt_pk_bf16_f32 v6, v8, v9
	v_cvt_pk_bf16_f32 v7, v10, v11
	global_store_dwordx4 v[2:3], v[4:7], off sc0 sc1
	s_andn2_b64 exec, exec, s[42:43]
	s_cbranch_execnz .LBB0_318

; DI void unpack8(const u32x4 w, float* x) { x[0] = bflo(w.x); x[1] = bfhi(w.x); x[2] = bflo(w.y); x[3] = bfhi(w.y); x[4] = bflo(w.z); x[5] = bfhi(w.z); x[6] = bflo(w.w); x[7] = bfhi(w.w); }
; DI u32x4 pack8(const float* x) { u32x4 w; w.x = pk2(x[0], x[1]); w.y = pk2(x[2], x[3]); w.z = pk2(x[4], x[5]); w.w = pk2(x[6], x[7]); return w; }
; DI void combine_c(const bf16_t* OC, bf16_t* AO, const float* sub_gain, float lam, float oml, int gtid, int gthreads) {
;     for (int idx = gtid; idx < TC * 128; idx += gthreads) {
;         const int j = idx & 15, h = (idx >> 4) & 7, row = idx >> 7;
;         const __attribute__((address_space(1))) bf16_t* p = (const __attribute__((address_space(1))) bf16_t*)OC + (size_t)row * 2048 + h * 256 + j * 8;
;         float a[8], b[8], y[8]; unpack8(*(const __attribute__((address_space(1))) u32x4*)p, a); unpack8(*(const __attribute__((address_space(1))) u32x4*)(p + 128), b);
;         float ss = 0.f;
; #pragma unroll
;         for (int e = 0; e < 8; ++e) { a[e] = a[e] - lam * b[e]; ss += a[e] * a[e]; }
;         ss += __shfl_xor(ss, 1); ss += __shfl_xor(ss, 2); ss += __shfl_xor(ss, 4); ss += __shfl_xor(ss, 8);
;         const float rstd = 1.0f / sqrtf(ss * (1.f / 128.f) + NORM_EPS) * oml;
; #pragma unroll
;         for (int e = 0; e < 8; ++e) y[e] = a[e] * rstd * sub_gain[8 * j + e];
;         *(__attribute__((address_space(1))) u32x4*)((__attribute__((address_space(1))) bf16_t*)AO + (size_t)row * 1024 + h * 128 + j * 8) = pack8(y);
;     }
.LBB0_325:
	v_ashrrev_i32_e32 v24, 7, v202
	v_ashrrev_i32_e32 v25, 31, v24
	v_bfe_u32 v7, v202, 4, 3
	v_lshlrev_b64 v[10:11], 12, v[24:25]
	v_mov_b32_e32 v9, v195
	v_and_b32_e32 v16, 0x78, v6
	v_lshlrev_b32_e32 v8, 9, v7
	v_lshl_add_u64 v[10:11], s[30:31], 0, v[10:11]
	v_mov_b32_e32 v27, v195
	v_lshlrev_b32_e32 v26, 1, v16
	v_lshl_add_u64 v[8:9], v[10:11], 0, v[8:9]
	v_lshl_add_u64 v[12:13], v[8:9], 0, v[26:27]
	global_load_dwordx4 v[8:11], v[12:13], off
	s_nop 0
	global_load_dwordx4 v[12:15], v[12:13], off offset:256
	v_lshlrev_b32_e32 v194, 8, v7
	v_lshlrev_b32_e32 v7, 2, v16
	global_load_dwordx4 v[16:19], v7, s[12:13] offset:16
	global_load_dwordx4 v[20:23], v7, s[12:13]
	v_lshlrev_b64 v[24:25], 11, v[24:25]
	v_lshl_add_u64 v[24:25], s[72:73], 0, v[24:25]
	v_lshl_add_u64 v[24:25], v[24:25], 0, v[194:195]
	v_lshl_add_u64 v[24:25], v[24:25], 0, v[26:27]
	v_add_u32_e32 v202, s64, v202
	s_mov_b32 s0, 0x1fffff
	v_cmp_lt_i32_e32 vcc, s0, v202
	s_or_b64 s[36:37], vcc, s[36:37]
	v_add_u32_e32 v6, s66, v6
	s_waitcnt vmcnt(3)
	v_lshlrev_b32_e32 v26, 16, v11
	v_and_b32_e32 v27, 0xffff0000, v11
	s_waitcnt vmcnt(2)
	v_lshlrev_b32_e32 v28, 16, v15
	v_and_b32_e32 v29, 0xffff0000, v15
	v_lshlrev_b32_e32 v30, 16, v10
	v_and_b32_e32 v31, 0xffff0000, v10
	v_lshlrev_b32_e32 v10, 16, v14
	v_and_b32_e32 v11, 0xffff0000, v14
	v_lshlrev_b32_e32 v14, 16, v9
	v_and_b32_e32 v15, 0xffff0000, v9
	v_lshlrev_b32_e32 v34, 16, v8
	v_and_b32_e32 v35, 0xffff0000, v8
	v_lshlrev_b32_e32 v8, 16, v12
	v_and_b32_e32 v9, 0xffff0000, v12
	v_lshlrev_b32_e32 v32, 16, v13
	v_and_b32_e32 v33, 0xffff0000, v13
	v_pk_fma_f32 v[8:9], v[0:1], v[8:9], v[34:35] neg_lo:[1,0,0] neg_hi:[1,0,0]
	v_pk_fma_f32 v[14:15], v[0:1], v[32:33], v[14:15] neg_lo:[1,0,0] neg_hi:[1,0,0]
	v_pk_mul_f32 v[32:33], v[8:9], v[8:9]
	v_pk_fma_f32 v[10:11], v[0:1], v[10:11], v[30:31] neg_lo:[1,0,0] neg_hi:[1,0,0]
	v_pk_mul_f32 v[30:31], v[14:15], v[14:15]
	v_add_f32_e32 v7, v32, v33
	v_add_f32_e32 v7, v30, v7
	v_pk_fma_f32 v[12:13], v[0:1], v[28:29], v[26:27] neg_lo:[1,0,0] neg_hi:[1,0,0]
	v_pk_mul_f32 v[28:29], v[10:11], v[10:11]
	v_add_f32_e32 v7, v31, v7
	v_add_f32_e32 v7, v28, v7
	v_pk_mul_f32 v[26:27], v[12:13], v[12:13]
	v_add_f32_e32 v7, v29, v7
	v_add_f32_e32 v7, v26, v7
	v_add_f32_e32 v7, v27, v7
	ds_bpermute_b32 v26, v2, v7
	s_waitcnt lgkmcnt(0)
	v_add_f32_e32 v7, v7, v26
	ds_bpermute_b32 v26, v3, v7
	s_waitcnt lgkmcnt(0)
	v_add_f32_e32 v7, v7, v26
	ds_bpermute_b32 v26, v4, v7
	s_waitcnt lgkmcnt(0)
	v_add_f32_e32 v7, v7, v26
	ds_bpermute_b32 v26, v5, v7
	s_waitcnt lgkmcnt(0)
	v_add_f32_e32 v7, v7, v26
	v_fmamk_f32 v7, v7, 0x3c000000, v237
	v_mul_f32_e32 v26, 0x4f800000, v7
	v_cmp_gt_f32_e32 vcc, s68, v7
	s_nop 1
	v_cndmask_b32_e32 v7, v7, v26, vcc
	v_sqrt_f32_e32 v26, v7
	s_nop 0
	v_add_u32_e32 v27, -1, v26
	v_add_u32_e32 v28, 1, v26
	v_fma_f32 v29, -v27, v26, v7
	v_fma_f32 v30, -v28, v26, v7
	v_cmp_ge_f32_e64 s[0:1], 0, v29
	s_nop 1
	v_cndmask_b32_e64 v26, v26, v27, s[0:1]
	v_cmp_lt_f32_e64 s[0:1], 0, v30
	s_nop 1
	v_cndmask_b32_e64 v26, v26, v28, s[0:1]
	v_mul_f32_e32 v27, 0x37800000, v26
	v_cndmask_b32_e32 v26, v26, v27, vcc
	v_cmp_class_f32_e32 vcc, v7, v238
	s_nop 1
	v_cndmask_b32_e32 v7, v26, v7, vcc
	v_div_scale_f32 v26, s[0:1], v7, v7, 1.0
	v_rcp_f32_e32 v28, v26
	v_div_scale_f32 v27, vcc, 1.0, v7, 1.0
	v_fma_f32 v29, -v26, v28, 1.0
	v_fmac_f32_e32 v28, v29, v28
	v_mul_f32_e32 v29, v27, v28
	v_fma_f32 v30, -v26, v29, v27
	v_fmac_f32_e32 v29, v30, v28
	v_fma_f32 v26, -v26, v29, v27
	v_div_fmas_f32 v26, v26, v28, v29
	v_div_fixup_f32 v7, v26, v7, 1.0
	v_mul_f32_e32 v26, s67, v7
	v_pk_mul_f32 v[8:9], v[8:9], v[26:27] op_sel_hi:[1,0]
	v_pk_mul_f32 v[14:15], v[14:15], v[26:27] op_sel_hi:[1,0]
	v_pk_mul_f32 v[10:11], v[10:11], v[26:27] op_sel_hi:[1,0]
	v_pk_mul_f32 v[12:13], v[12:13], v[26:27] op_sel_hi:[1,0]
	s_waitcnt vmcnt(0)
	v_pk_mul_f32 v[8:9], v[20:21], v[8:9]
	v_pk_mul_f32 v[14:15], v[22:23], v[14:15]
	v_pk_mul_f32 v[10:11], v[16:17], v[10:11]
	v_pk_mul_f32 v[12:13], v[18:19], v[12:13]
	v_cvt_pk_bf16_f32 v8, v8, v9
	v_cvt_pk_bf16_f32 v9, v14, v15
	v_cvt_pk_bf16_f32 v10, v10, v11
	v_cvt_pk_bf16_f32 v11, v12, v13
	global_store_dwordx4 v[24:25], v[8:11], off sc0 sc1
	s_andn2_b64 exec, exec, s[36:37]
	s_cbranch_execnz .LBB0_325

; #define PG8_GAS __attribute__((address_space(1)))
; __device__ __forceinline__ unsigned cvt_pk_bf16(float lo, float hi) { unsigned r; asm volatile("v_cvt_pk_bf16_f32 %0, %1, %2" : "=v"(r) : "v"(lo), "v"(hi)); return r; }
;     __device__ __forceinline__ void operator()(const f32x4 (&acc)[2][2][4][2], const Unit& u, int wr, int wc, int fr, int fq) const {
;     ...
;                 for (int bj = 0; bj < 2; ++bj) pre[ai][m][bj] = *(const PG8_GAS u32x4*)(XBg + (size_t)(row0 + ai * HALF + m * 16) * ldc + col0 + bj * HALF);
; #pragma unroll
;         for (int ai = 0; ai < 2; ++ai)
; #pragma unroll
;             for (int m = 0; m < 4; ++m) { const int row = row0 + ai * HALF + m * 16; PG8_GAS bf16_t* rowb = XBg + (size_t)row * ldc + col0;
;                 float sq = 0.f;
; #pragma unroll
;                 for (int bj = 0; bj < 2; ++bj) { const u32x4 o = pre[ai][m][bj]; const f32x4 c0 = acc[ai][bj][m][0], c1 = acc[ai][bj][m][1];
;                     u32x4 w; w.x = cvt_pk_bf16(__uint_as_float(o.x << 16) + c0[0], __uint_as_float(o.x & 0xffff0000u) + c0[1]); w.y = cvt_pk_bf16(__uint_as_float(o.y << 16) + c0[2], __uint_as_float(o.y & 0xffff0000u) + c0[3]);
;                     w.z = cvt_pk_bf16(__uint_as_float(o.z << 16) + c1[0], __uint_as_float(o.z & 0xffff0000u) + c1[1]); w.w = cvt_pk_bf16(__uint_as_float(o.w << 16) + c1[2], __uint_as_float(o.w & 0xffff0000u) + c1[3]);
;                     *(PG8_GAS u32x4*)(rowb + bj * HALF) = w;
;                     const float a0 = __uint_as_float(w.x << 16), a1 = __uint_as_float(w.x & 0xffff0000u), a2 = __uint_as_float(w.y << 16), a3 = __uint_as_float(w.y & 0xffff0000u);
;                     const float b0 = __uint_as_float(w.z << 16), b1 = __uint_as_float(w.z & 0xffff0000u), b2 = __uint_as_float(w.w << 16), b3 = __uint_as_float(w.w & 0xffff0000u);
;                     sq += (a0 * a0 + a1 * a1) + (a2 * a2 + a3 * a3) + (b0 * b0 + b1 * b1) + (b2 * b2 + b3 * b3); }
;                 sq += __shfl_xor(sq, 16); sq += __shfl_xor(sq, 32);
;                 if (fq == 0) __hip_atomic_fetch_add(ssg + row, (unsigned long long)(sq * 1048576.0f + 0.5f), __ATOMIC_RELAXED, __HIP_MEMORY_SCOPE_AGENT); }
.LBB0_383:
	v_lshl_add_u32 v222, s76, 8, v196
	v_lshl_or_b32 v124, s57, 8, v250
	v_ashrrev_i32_e32 v125, 31, v124
	v_ashrrev_i32_e32 v223, 31, v222
	v_lshl_add_u64 v[124:125], v[124:125], 1, s[14:15]
	v_lshlrev_b64 v[126:127], 11, v[222:223]
	v_lshl_add_u64 v[224:225], v[124:125], 0, v[126:127]
	global_load_dwordx4 v[188:191], v[224:225], off
	global_load_dwordx4 v[184:187], v[224:225], off offset:256
	v_or_b32_e32 v126, 16, v222
	v_ashrrev_i32_e32 v127, 31, v126
	v_lshlrev_b64 v[126:127], 11, v[126:127]
	v_lshl_add_u64 v[220:221], v[124:125], 0, v[126:127]
	v_or_b32_e32 v126, 32, v222
	v_ashrrev_i32_e32 v127, 31, v126
	v_lshlrev_b64 v[126:127], 11, v[126:127]
	v_lshl_add_u64 v[218:219], v[124:125], 0, v[126:127]
	v_or_b32_e32 v126, 48, v222
	v_ashrrev_i32_e32 v127, 31, v126
	s_mov_b64 s[40:41], 0x40000
	v_lshlrev_b64 v[126:127], 11, v[126:127]
	v_lshl_add_u64 v[214:215], v[224:225], 0, s[40:41]
	s_mov_b32 s40, 0x40000
	v_lshl_add_u64 v[216:217], v[124:125], 0, v[126:127]
	v_add_co_u32_e32 v124, vcc, s40, v224
	s_mov_b64 s[40:41], 0x48000
	s_nop 0
	v_addc_co_u32_e32 v125, vcc, 0, v225, vcc
	v_lshl_add_u64 v[212:213], v[224:225], 0, s[40:41]
	s_mov_b32 s40, 0x48000
	global_load_dwordx4 v[180:183], v[220:221], off
	global_load_dwordx4 v[176:179], v[220:221], off offset:256
	global_load_dwordx4 v[172:175], v[218:219], off
	global_load_dwordx4 v[168:171], v[218:219], off offset:256
	global_load_dwordx4 v[164:167], v[216:217], off
	global_load_dwordx4 v[156:159], v[216:217], off offset:256
	global_load_dwordx4 v[160:163], v[124:125], off
	global_load_dwordx4 v[152:155], v[214:215], off offset:256
	v_add_co_u32_e32 v124, vcc, s40, v224
	s_mov_b64 s[40:41], 0x50000
	s_nop 0
	v_addc_co_u32_e32 v125, vcc, 0, v225, vcc
	v_lshl_add_u64 v[210:211], v[224:225], 0, s[40:41]
	s_mov_b32 s40, 0x50000
	global_load_dwordx4 v[148:151], v[124:125], off
	global_load_dwordx4 v[144:147], v[212:213], off offset:256
	v_add_co_u32_e32 v124, vcc, s40, v224
	s_mov_b64 s[40:41], 0x58000
	s_nop 0
	v_addc_co_u32_e32 v125, vcc, 0, v225, vcc
	v_lshl_add_u64 v[208:209], v[224:225], 0, s[40:41]
	s_mov_b32 s40, 0x58000
	global_load_dwordx4 v[140:143], v[124:125], off
	global_load_dwordx4 v[128:131], v[210:211], off offset:256
	v_add_co_u32_e32 v124, vcc, s40, v224
	s_waitcnt vmcnt(0)
	v_lshlrev_b32_e32 v242, 16, v188
	v_addc_co_u32_e32 v125, vcc, 0, v225, vcc
	global_load_dwordx4 v[132:135], v[124:125], off
	s_nop 0
	global_load_dwordx4 v[124:127], v[208:209], off offset:256
	v_and_b32_e32 v188, 0xffff0000, v188
	v_add_f32_e32 v136, v136, v242
	v_add_f32_e32 v137, v137, v188
	v_cvt_pk_bf16_f32 v136, v136, v137
	v_lshlrev_b32_e32 v137, 16, v189
	v_add_f32_e32 v137, v138, v137
	v_and_b32_e32 v138, 0xffff0000, v189
	v_add_f32_e32 v138, v139, v138
	v_cvt_pk_bf16_f32 v137, v137, v138
	v_lshlrev_b32_e32 v138, 16, v190
	v_add_f32_e32 v120, v120, v138
	v_and_b32_e32 v138, 0xffff0000, v190
	v_add_f32_e32 v121, v121, v138
	v_cvt_pk_bf16_f32 v138, v120, v121
	v_and_b32_e32 v121, 0xffff0000, v191
	v_lshlrev_b32_e32 v120, 16, v191
	v_add_f32_e32 v121, v123, v121
	v_add_f32_e32 v120, v122, v120
	v_cvt_pk_bf16_f32 v139, v120, v121
	v_and_b32_e32 v121, 0xffff0000, v136
	v_lshlrev_b32_e32 v120, 16, v136
	v_and_b32_e32 v123, 0xffff0000, v137
	v_mul_f32_e32 v121, v121, v121
	v_lshlrev_b32_e32 v122, 16, v137
	v_fmac_f32_e32 v121, v120, v120
	v_mul_f32_e32 v120, v123, v123
	global_store_dwordx4 v[224:225], v[136:139], off sc0 sc1
	v_fmac_f32_e32 v120, v122, v122
	v_add_f32_e32 v120, v121, v120
	v_and_b32_e32 v137, 0xffff0000, v138
	v_lshlrev_b32_e32 v136, 16, v138
	v_mul_f32_e32 v121, v137, v137
	v_lshlrev_b32_e32 v138, 16, v139
	v_and_b32_e32 v139, 0xffff0000, v139
	v_fmac_f32_e32 v121, v136, v136
	v_add_f32_e32 v120, v120, v121
	v_mul_f32_e32 v121, v139, v139
	v_fmac_f32_e32 v121, v138, v138
	v_add_f32_e32 v120, v120, v121
	v_lshlrev_b32_e32 v121, 16, v184
	v_add_f32_e32 v116, v116, v121
	v_and_b32_e32 v121, 0xffff0000, v184
	v_add_f32_e32 v117, v117, v121
	v_cvt_pk_bf16_f32 v116, v116, v117
	v_lshlrev_b32_e32 v117, 16, v185
	v_add_f32_e32 v117, v118, v117
	v_and_b32_e32 v118, 0xffff0000, v185
	v_add_f32_e32 v118, v119, v118
	v_cvt_pk_bf16_f32 v117, v117, v118
	v_lshlrev_b32_e32 v118, 16, v186
	v_add_f32_e32 v112, v112, v118
	v_and_b32_e32 v118, 0xffff0000, v186
	v_add_f32_e32 v113, v113, v118
	v_cvt_pk_bf16_f32 v118, v112, v113
	v_and_b32_e32 v113, 0xffff0000, v187
	v_lshlrev_b32_e32 v112, 16, v187
	v_add_f32_e32 v113, v115, v113
	v_add_f32_e32 v112, v114, v112
	v_cvt_pk_bf16_f32 v119, v112, v113
	v_and_b32_e32 v113, 0xffff0000, v116
	v_lshlrev_b32_e32 v112, 16, v116
	v_and_b32_e32 v115, 0xffff0000, v117
	v_mul_f32_e32 v113, v113, v113
	v_lshlrev_b32_e32 v114, 16, v117
	v_fmac_f32_e32 v113, v112, v112
	v_mul_f32_e32 v112, v115, v115
	global_store_dwordx4 v[224:225], v[116:119], off offset:256 sc0 sc1
	v_fmac_f32_e32 v112, v114, v114
	v_add_f32_e32 v112, v113, v112
	v_and_b32_e32 v117, 0xffff0000, v118
	v_lshlrev_b32_e32 v116, 16, v118
	v_mul_f32_e32 v113, v117, v117
	v_lshlrev_b32_e32 v118, 16, v119
	v_and_b32_e32 v119, 0xffff0000, v119
	v_fmac_f32_e32 v113, v116, v116
	v_add_f32_e32 v112, v112, v113
	v_mul_f32_e32 v113, v119, v119
	v_fmac_f32_e32 v113, v118, v118
	v_cmp_lt_i32_e32 vcc, v245, v240
	v_add_f32_e32 v112, v112, v113
	v_add_f32_e32 v112, v120, v112
	v_cndmask_b32_e32 v113, v239, v245, vcc
	v_lshlrev_b32_e32 v114, 2, v113
	ds_bpermute_b32 v113, v114, v112
	v_cmp_lt_i32_e32 vcc, v246, v240
	s_waitcnt lgkmcnt(0)
	v_add_f32_e32 v116, v112, v113
	v_cndmask_b32_e32 v112, v239, v246, vcc
	v_lshlrev_b32_e32 v115, 2, v112
	ds_bpermute_b32 v117, v115, v116
	v_lshl_add_u64 v[112:113], v[222:223], 3, s[54:55]
	s_and_saveexec_b64 s[40:41], s[38:39]
	s_cbranch_execz .LBB0_385
	s_waitcnt lgkmcnt(0)
	v_add_f32_e32 v116, v116, v117
	v_fma_f32 v116, v116, s80, 0.5
	v_trunc_f32_e32 v116, v116
	v_mul_f32_e32 v117, 0x2f800000, v116
	v_floor_f32_e32 v117, v117
	v_fmac_f32_e32 v116, 0xcf800000, v117
	v_cvt_u32_f32_e32 v116, v116
	v_cvt_u32_f32_e32 v117, v117
	global_atomic_add_x2 v[112:113], v[116:117], off
; #define PG8_GAS __attribute__((address_space(1)))
; __device__ __forceinline__ unsigned cvt_pk_bf16(float lo, float hi) { unsigned r; asm volatile("v_cvt_pk_bf16_f32 %0, %1, %2" : "=v"(r) : "v"(lo), "v"(hi)); return r; }
;     __device__ __forceinline__ void operator()(const f32x4 (&acc)[2][2][4][2], const Unit& u, int wr, int wc, int fr, int fq) const {
;     ...
;         for (int ai = 0; ai < 2; ++ai)
; #pragma unroll
;             for (int m = 0; m < 4; ++m) { const int row = row0 + ai * HALF + m * 16; PG8_GAS bf16_t* rowb = XBg + (size_t)row * ldc + col0;
;                 float sq = 0.f;
; #pragma unroll
;                 for (int bj = 0; bj < 2; ++bj) { const u32x4 o = pre[ai][m][bj]; const f32x4 c0 = acc[ai][bj][m][0], c1 = acc[ai][bj][m][1];
;                     u32x4 w; w.x = cvt_pk_bf16(__uint_as_float(o.x << 16) + c0[0], __uint_as_float(o.x & 0xffff0000u) + c0[1]); w.y = cvt_pk_bf16(__uint_as_float(o.y << 16) + c0[2], __uint_as_float(o.y & 0xffff0000u) + c0[3]);
;                     w.z = cvt_pk_bf16(__uint_as_float(o.z << 16) + c1[0], __uint_as_float(o.z & 0xffff0000u) + c1[1]); w.w = cvt_pk_bf16(__uint_as_float(o.w << 16) + c1[2], __uint_as_float(o.w & 0xffff0000u) + c1[3]);
;                     *(PG8_GAS u32x4*)(rowb + bj * HALF) = w;
;                     const float a0 = __uint_as_float(w.x << 16), a1 = __uint_as_float(w.x & 0xffff0000u), a2 = __uint_as_float(w.y << 16), a3 = __uint_as_float(w.y & 0xffff0000u);
;                     const float b0 = __uint_as_float(w.z << 16), b1 = __uint_as_float(w.z & 0xffff0000u), b2 = __uint_as_float(w.w << 16), b3 = __uint_as_float(w.w & 0xffff0000u);
;                     sq += (a0 * a0 + a1 * a1) + (a2 * a2 + a3 * a3) + (b0 * b0 + b1 * b1) + (b2 * b2 + b3 * b3); }
;                 sq += __shfl_xor(sq, 16); sq += __shfl_xor(sq, 32);
;                 if (fq == 0) __hip_atomic_fetch_add(ssg + row, (unsigned long long)(sq * 1048576.0f + 0.5f), __ATOMIC_RELAXED, __HIP_MEMORY_SCOPE_AGENT); }
.LBB0_385:
	s_or_b64 exec, exec, s[40:41]
	v_lshlrev_b32_e32 v116, 16, v180
	v_add_f32_e32 v108, v108, v116
	v_and_b32_e32 v116, 0xffff0000, v180
	v_add_f32_e32 v109, v109, v116
	v_cvt_pk_bf16_f32 v108, v108, v109
	v_lshlrev_b32_e32 v109, 16, v181
	v_add_f32_e32 v109, v110, v109
	v_and_b32_e32 v110, 0xffff0000, v181
	v_add_f32_e32 v110, v111, v110
	v_cvt_pk_bf16_f32 v109, v109, v110
	v_lshlrev_b32_e32 v110, 16, v182
	v_add_f32_e32 v104, v104, v110
	v_and_b32_e32 v110, 0xffff0000, v182
	v_add_f32_e32 v105, v105, v110
	v_cvt_pk_bf16_f32 v110, v104, v105
	v_and_b32_e32 v105, 0xffff0000, v183
	v_lshlrev_b32_e32 v104, 16, v183
	v_add_f32_e32 v105, v107, v105
	v_add_f32_e32 v104, v106, v104
	v_cvt_pk_bf16_f32 v111, v104, v105
	v_and_b32_e32 v105, 0xffff0000, v108
	v_lshlrev_b32_e32 v104, 16, v108
	v_and_b32_e32 v107, 0xffff0000, v109
	v_mul_f32_e32 v105, v105, v105
	v_lshlrev_b32_e32 v106, 16, v109
	v_fmac_f32_e32 v105, v104, v104
	v_mul_f32_e32 v104, v107, v107
	global_store_dwordx4 v[220:221], v[108:111], off sc0 sc1
	v_fmac_f32_e32 v104, v106, v106
	v_add_f32_e32 v104, v105, v104
	v_and_b32_e32 v109, 0xffff0000, v110
	v_lshlrev_b32_e32 v108, 16, v110
	v_mul_f32_e32 v105, v109, v109
	v_lshlrev_b32_e32 v110, 16, v111
	v_and_b32_e32 v111, 0xffff0000, v111
	v_fmac_f32_e32 v105, v108, v108
	v_add_f32_e32 v104, v104, v105
	v_mul_f32_e32 v105, v111, v111
	v_fmac_f32_e32 v105, v110, v110
	v_add_f32_e32 v104, v104, v105
	v_lshlrev_b32_e32 v105, 16, v176
	v_add_f32_e32 v100, v100, v105
	v_and_b32_e32 v105, 0xffff0000, v176
	v_add_f32_e32 v101, v101, v105
	v_cvt_pk_bf16_f32 v100, v100, v101
	v_lshlrev_b32_e32 v101, 16, v177
	v_add_f32_e32 v101, v102, v101
	v_and_b32_e32 v102, 0xffff0000, v177
	v_add_f32_e32 v102, v103, v102
	v_cvt_pk_bf16_f32 v101, v101, v102
	v_lshlrev_b32_e32 v102, 16, v178
	v_add_f32_e32 v96, v96, v102
	v_and_b32_e32 v102, 0xffff0000, v178
	v_add_f32_e32 v97, v97, v102
	v_cvt_pk_bf16_f32 v102, v96, v97
	v_and_b32_e32 v97, 0xffff0000, v179
	v_lshlrev_b32_e32 v96, 16, v179
	v_add_f32_e32 v97, v99, v97
	v_add_f32_e32 v96, v98, v96
	v_cvt_pk_bf16_f32 v103, v96, v97
	v_and_b32_e32 v97, 0xffff0000, v100
	v_lshlrev_b32_e32 v96, 16, v100
	v_and_b32_e32 v99, 0xffff0000, v101
	v_mul_f32_e32 v97, v97, v97
	v_lshlrev_b32_e32 v98, 16, v101
	v_fmac_f32_e32 v97, v96, v96
	v_mul_f32_e32 v96, v99, v99
	v_and_b32_e32 v106, 0xffff0000, v102
	v_fmac_f32_e32 v96, v98, v98
	v_lshlrev_b32_e32 v105, 16, v102
	v_add_f32_e32 v96, v97, v96
	v_mul_f32_e32 v97, v106, v106
	v_and_b32_e32 v108, 0xffff0000, v103
	v_fmac_f32_e32 v97, v105, v105
	v_lshlrev_b32_e32 v107, 16, v103
	v_add_f32_e32 v96, v96, v97
	v_mul_f32_e32 v97, v108, v108
	v_fmac_f32_e32 v97, v107, v107
	v_add_f32_e32 v96, v96, v97
	v_add_f32_e32 v96, v104, v96
	ds_bpermute_b32 v97, v114, v96
	global_store_dwordx4 v[220:221], v[100:103], off offset:256 sc0 sc1
	s_waitcnt lgkmcnt(0)
	v_add_f32_e32 v96, v96, v97
	ds_bpermute_b32 v97, v115, v96
	s_and_saveexec_b64 s[40:41], s[38:39]
	s_cbranch_execz .LBB0_387
	s_waitcnt lgkmcnt(0)
	v_add_f32_e32 v96, v96, v97
	v_fma_f32 v96, v96, s80, 0.5
	v_trunc_f32_e32 v96, v96
	v_mul_f32_e32 v97, 0x2f800000, v96
	v_floor_f32_e32 v97, v97
	v_fmac_f32_e32 v96, 0xcf800000, v97
	v_cvt_u32_f32_e32 v96, v96
	v_cvt_u32_f32_e32 v97, v97
	global_atomic_add_x2 v[112:113], v[96:97], off offset:128
.LBB0_387:
	s_or_b64 exec, exec, s[40:41]
	v_lshlrev_b32_e32 v96, 16, v172
	v_add_f32_e32 v92, v92, v96
	v_and_b32_e32 v96, 0xffff0000, v172
	v_add_f32_e32 v93, v93, v96
	v_cvt_pk_bf16_f32 v92, v92, v93
	v_lshlrev_b32_e32 v93, 16, v173
	v_add_f32_e32 v93, v94, v93
	v_and_b32_e32 v94, 0xffff0000, v173
	v_add_f32_e32 v94, v95, v94
	v_cvt_pk_bf16_f32 v93, v93, v94
	v_lshlrev_b32_e32 v94, 16, v174
	v_add_f32_e32 v88, v88, v94
	v_and_b32_e32 v94, 0xffff0000, v174
	v_add_f32_e32 v89, v89, v94
	v_cvt_pk_bf16_f32 v94, v88, v89
	v_and_b32_e32 v89, 0xffff0000, v175
	v_lshlrev_b32_e32 v88, 16, v175
	v_add_f32_e32 v89, v91, v89
	v_add_f32_e32 v88, v90, v88
	v_cvt_pk_bf16_f32 v95, v88, v89
	v_and_b32_e32 v89, 0xffff0000, v92
	v_lshlrev_b32_e32 v88, 16, v92
	v_and_b32_e32 v91, 0xffff0000, v93
	v_mul_f32_e32 v89, v89, v89
	v_lshlrev_b32_e32 v90, 16, v93
	v_fmac_f32_e32 v89, v88, v88
	v_mul_f32_e32 v88, v91, v91
	global_store_dwordx4 v[218:219], v[92:95], off sc0 sc1
	v_fmac_f32_e32 v88, v90, v90
	v_add_f32_e32 v88, v89, v88
	v_and_b32_e32 v93, 0xffff0000, v94
	v_lshlrev_b32_e32 v92, 16, v94
	v_mul_f32_e32 v89, v93, v93
	v_lshlrev_b32_e32 v94, 16, v95
	v_and_b32_e32 v95, 0xffff0000, v95
	v_fmac_f32_e32 v89, v92, v92
	v_add_f32_e32 v88, v88, v89
	v_mul_f32_e32 v89, v95, v95
	v_fmac_f32_e32 v89, v94, v94
	v_add_f32_e32 v88, v88, v89
	v_lshlrev_b32_e32 v89, 16, v168
	v_add_f32_e32 v84, v84, v89
	v_and_b32_e32 v89, 0xffff0000, v168
	v_add_f32_e32 v85, v85, v89
	v_cvt_pk_bf16_f32 v84, v84, v85
	v_lshlrev_b32_e32 v85, 16, v169
	v_add_f32_e32 v85, v86, v85
	v_and_b32_e32 v86, 0xffff0000, v169
	v_add_f32_e32 v86, v87, v86
	v_cvt_pk_bf16_f32 v85, v85, v86
	v_lshlrev_b32_e32 v86, 16, v170
	v_add_f32_e32 v80, v80, v86
	v_and_b32_e32 v86, 0xffff0000, v170
	v_add_f32_e32 v81, v81, v86
	v_cvt_pk_bf16_f32 v86, v80, v81
	v_and_b32_e32 v81, 0xffff0000, v171
	v_lshlrev_b32_e32 v80, 16, v171
	v_add_f32_e32 v81, v83, v81
	v_add_f32_e32 v80, v82, v80
	v_cvt_pk_bf16_f32 v87, v80, v81
	v_and_b32_e32 v81, 0xffff0000, v84
	v_lshlrev_b32_e32 v80, 16, v84
	v_and_b32_e32 v83, 0xffff0000, v85
	v_mul_f32_e32 v81, v81, v81
	v_lshlrev_b32_e32 v82, 16, v85
	v_fmac_f32_e32 v81, v80, v80
	v_mul_f32_e32 v80, v83, v83
	v_and_b32_e32 v90, 0xffff0000, v86
	v_fmac_f32_e32 v80, v82, v82
	v_lshlrev_b32_e32 v89, 16, v86
	v_add_f32_e32 v80, v81, v80
	v_mul_f32_e32 v81, v90, v90
	v_and_b32_e32 v92, 0xffff0000, v87
	v_fmac_f32_e32 v81, v89, v89
	v_lshlrev_b32_e32 v91, 16, v87
	v_add_f32_e32 v80, v80, v81
	v_mul_f32_e32 v81, v92, v92
	v_fmac_f32_e32 v81, v91, v91
	v_add_f32_e32 v80, v80, v81
	v_add_f32_e32 v80, v88, v80
	ds_bpermute_b32 v81, v114, v80
	global_store_dwordx4 v[218:219], v[84:87], off offset:256 sc0 sc1
	s_waitcnt lgkmcnt(0)
	v_add_f32_e32 v80, v80, v81
	ds_bpermute_b32 v81, v115, v80
	s_and_saveexec_b64 s[40:41], s[38:39]
	s_cbranch_execz .LBB0_389
	s_waitcnt lgkmcnt(0)
	v_add_f32_e32 v80, v80, v81
	v_fma_f32 v80, v80, s80, 0.5
	v_trunc_f32_e32 v80, v80
	v_mul_f32_e32 v81, 0x2f800000, v80
	v_floor_f32_e32 v81, v81
	v_fmac_f32_e32 v80, 0xcf800000, v81
	v_cvt_u32_f32_e32 v80, v80
	v_cvt_u32_f32_e32 v81, v81
	global_atomic_add_x2 v[112:113], v[80:81], off offset:256
; #define PG8_GAS __attribute__((address_space(1)))
; __device__ __forceinline__ unsigned cvt_pk_bf16(float lo, float hi) { unsigned r; asm volatile("v_cvt_pk_bf16_f32 %0, %1, %2" : "=v"(r) : "v"(lo), "v"(hi)); return r; }
;     __device__ __forceinline__ void operator()(const f32x4 (&acc)[2][2][4][2], const Unit& u, int wr, int wc, int fr, int fq) const {
;     ...
;         for (int ai = 0; ai < 2; ++ai)
; #pragma unroll
;             for (int m = 0; m < 4; ++m) { const int row = row0 + ai * HALF + m * 16; PG8_GAS bf16_t* rowb = XBg + (size_t)row * ldc + col0;
;                 float sq = 0.f;
; #pragma unroll
;                 for (int bj = 0; bj < 2; ++bj) { const u32x4 o = pre[ai][m][bj]; const f32x4 c0 = acc[ai][bj][m][0], c1 = acc[ai][bj][m][1];
;                     u32x4 w; w.x = cvt_pk_bf16(__uint_as_float(o.x << 16) + c0[0], __uint_as_float(o.x & 0xffff0000u) + c0[1]); w.y = cvt_pk_bf16(__uint_as_float(o.y << 16) + c0[2], __uint_as_float(o.y & 0xffff0000u) + c0[3]);
;                     w.z = cvt_pk_bf16(__uint_as_float(o.z << 16) + c1[0], __uint_as_float(o.z & 0xffff0000u) + c1[1]); w.w = cvt_pk_bf16(__uint_as_float(o.w << 16) + c1[2], __uint_as_float(o.w & 0xffff0000u) + c1[3]);
;                     *(PG8_GAS u32x4*)(rowb + bj * HALF) = w;
;                     const float a0 = __uint_as_float(w.x << 16), a1 = __uint_as_float(w.x & 0xffff0000u), a2 = __uint_as_float(w.y << 16), a3 = __uint_as_float(w.y & 0xffff0000u);
;                     const float b0 = __uint_as_float(w.z << 16), b1 = __uint_as_float(w.z & 0xffff0000u), b2 = __uint_as_float(w.w << 16), b3 = __uint_as_float(w.w & 0xffff0000u);
;                     sq += (a0 * a0 + a1 * a1) + (a2 * a2 + a3 * a3) + (b0 * b0 + b1 * b1) + (b2 * b2 + b3 * b3); }
;                 sq += __shfl_xor(sq, 16); sq += __shfl_xor(sq, 32);
;                 if (fq == 0) __hip_atomic_fetch_add(ssg + row, (unsigned long long)(sq * 1048576.0f + 0.5f), __ATOMIC_RELAXED, __HIP_MEMORY_SCOPE_AGENT); }
.LBB0_389:
	s_or_b64 exec, exec, s[40:41]
	v_lshlrev_b32_e32 v80, 16, v164
	v_add_f32_e32 v76, v76, v80
	v_and_b32_e32 v80, 0xffff0000, v164
	v_add_f32_e32 v77, v77, v80
	v_cvt_pk_bf16_f32 v76, v76, v77
	v_lshlrev_b32_e32 v77, 16, v165
	v_add_f32_e32 v77, v78, v77
	v_and_b32_e32 v78, 0xffff0000, v165
	v_add_f32_e32 v78, v79, v78
	v_cvt_pk_bf16_f32 v77, v77, v78
	v_lshlrev_b32_e32 v78, 16, v166
	v_add_f32_e32 v72, v72, v78
	v_and_b32_e32 v78, 0xffff0000, v166
	v_add_f32_e32 v73, v73, v78
	v_cvt_pk_bf16_f32 v78, v72, v73
	v_and_b32_e32 v73, 0xffff0000, v167
	v_lshlrev_b32_e32 v72, 16, v167
	v_add_f32_e32 v73, v75, v73
	v_add_f32_e32 v72, v74, v72
	v_cvt_pk_bf16_f32 v79, v72, v73
	v_and_b32_e32 v73, 0xffff0000, v76
	v_lshlrev_b32_e32 v72, 16, v76
	v_and_b32_e32 v75, 0xffff0000, v77
	v_mul_f32_e32 v73, v73, v73
	v_lshlrev_b32_e32 v74, 16, v77
	v_fmac_f32_e32 v73, v72, v72
	v_mul_f32_e32 v72, v75, v75
	global_store_dwordx4 v[216:217], v[76:79], off sc0 sc1
	v_fmac_f32_e32 v72, v74, v74
	v_add_f32_e32 v72, v73, v72
	v_and_b32_e32 v77, 0xffff0000, v78
	v_lshlrev_b32_e32 v76, 16, v78
	v_mul_f32_e32 v73, v77, v77
	v_lshlrev_b32_e32 v78, 16, v79
	v_and_b32_e32 v79, 0xffff0000, v79
	v_fmac_f32_e32 v73, v76, v76
	v_add_f32_e32 v72, v72, v73
	v_mul_f32_e32 v73, v79, v79
	v_fmac_f32_e32 v73, v78, v78
	v_add_f32_e32 v72, v72, v73
	v_lshlrev_b32_e32 v73, 16, v156
	v_add_f32_e32 v68, v68, v73
	v_and_b32_e32 v73, 0xffff0000, v156
	v_add_f32_e32 v69, v69, v73
	v_cvt_pk_bf16_f32 v68, v68, v69
	v_lshlrev_b32_e32 v69, 16, v157
	v_add_f32_e32 v69, v70, v69
	v_and_b32_e32 v70, 0xffff0000, v157
	v_add_f32_e32 v70, v71, v70
	v_cvt_pk_bf16_f32 v69, v69, v70
	v_lshlrev_b32_e32 v70, 16, v158
	v_add_f32_e32 v64, v64, v70
	v_and_b32_e32 v70, 0xffff0000, v158
	v_add_f32_e32 v65, v65, v70
	v_cvt_pk_bf16_f32 v70, v64, v65
	v_and_b32_e32 v65, 0xffff0000, v159
	v_lshlrev_b32_e32 v64, 16, v159
	v_add_f32_e32 v65, v67, v65
	v_add_f32_e32 v64, v66, v64
	v_cvt_pk_bf16_f32 v71, v64, v65
	v_and_b32_e32 v65, 0xffff0000, v68
	v_lshlrev_b32_e32 v64, 16, v68
	v_and_b32_e32 v67, 0xffff0000, v69
	v_mul_f32_e32 v65, v65, v65
	v_lshlrev_b32_e32 v66, 16, v69
	v_fmac_f32_e32 v65, v64, v64
	v_mul_f32_e32 v64, v67, v67
	v_and_b32_e32 v74, 0xffff0000, v70
	v_fmac_f32_e32 v64, v66, v66
	v_lshlrev_b32_e32 v73, 16, v70
	v_add_f32_e32 v64, v65, v64
	v_mul_f32_e32 v65, v74, v74
	v_and_b32_e32 v76, 0xffff0000, v71
	v_fmac_f32_e32 v65, v73, v73
	v_lshlrev_b32_e32 v75, 16, v71
	v_add_f32_e32 v64, v64, v65
	v_mul_f32_e32 v65, v76, v76
	v_fmac_f32_e32 v65, v75, v75
	v_add_f32_e32 v64, v64, v65
	v_add_f32_e32 v64, v72, v64
	ds_bpermute_b32 v65, v114, v64
	global_store_dwordx4 v[216:217], v[68:71], off offset:256 sc0 sc1
	s_waitcnt lgkmcnt(0)
	v_add_f32_e32 v64, v64, v65
	ds_bpermute_b32 v65, v115, v64
	s_and_saveexec_b64 s[40:41], s[38:39]
	s_cbranch_execz .LBB0_391
	s_waitcnt lgkmcnt(0)
	v_add_f32_e32 v64, v64, v65
	v_fma_f32 v64, v64, s80, 0.5
	v_trunc_f32_e32 v64, v64
	v_mul_f32_e32 v65, 0x2f800000, v64
	v_floor_f32_e32 v65, v65
	v_fmac_f32_e32 v64, 0xcf800000, v65
	v_cvt_u32_f32_e32 v64, v64
	v_cvt_u32_f32_e32 v65, v65
	global_atomic_add_x2 v[112:113], v[64:65], off offset:384
.LBB0_391:
	s_or_b64 exec, exec, s[40:41]
	v_lshlrev_b32_e32 v64, 16, v160
	v_add_f32_e32 v60, v60, v64
	v_and_b32_e32 v64, 0xffff0000, v160
	v_add_f32_e32 v61, v61, v64
	v_cvt_pk_bf16_f32 v60, v60, v61
	v_lshlrev_b32_e32 v61, 16, v161
	v_add_f32_e32 v61, v62, v61
	v_and_b32_e32 v62, 0xffff0000, v161
	v_add_f32_e32 v62, v63, v62
	v_cvt_pk_bf16_f32 v61, v61, v62
	v_lshlrev_b32_e32 v62, 16, v162
	v_add_f32_e32 v56, v56, v62
	v_and_b32_e32 v62, 0xffff0000, v162
	v_add_f32_e32 v57, v57, v62
	v_cvt_pk_bf16_f32 v62, v56, v57
	v_and_b32_e32 v57, 0xffff0000, v163
	v_lshlrev_b32_e32 v56, 16, v163
	v_add_f32_e32 v57, v59, v57
	v_add_f32_e32 v56, v58, v56
	v_cvt_pk_bf16_f32 v63, v56, v57
	v_and_b32_e32 v57, 0xffff0000, v60
	v_lshlrev_b32_e32 v56, 16, v60
	v_and_b32_e32 v59, 0xffff0000, v61
	v_mul_f32_e32 v57, v57, v57
	v_lshlrev_b32_e32 v58, 16, v61
	v_fmac_f32_e32 v57, v56, v56
	v_mul_f32_e32 v56, v59, v59
	global_store_dwordx4 v[214:215], v[60:63], off sc0 sc1
	v_fmac_f32_e32 v56, v58, v58
	v_add_f32_e32 v56, v57, v56
	v_and_b32_e32 v61, 0xffff0000, v62
	v_lshlrev_b32_e32 v60, 16, v62
	v_mul_f32_e32 v57, v61, v61
	v_lshlrev_b32_e32 v62, 16, v63
	v_and_b32_e32 v63, 0xffff0000, v63
	v_fmac_f32_e32 v57, v60, v60
	v_add_f32_e32 v56, v56, v57
	v_mul_f32_e32 v57, v63, v63
	v_fmac_f32_e32 v57, v62, v62
	v_add_f32_e32 v56, v56, v57
	v_lshlrev_b32_e32 v57, 16, v152
	v_add_f32_e32 v52, v52, v57
	v_and_b32_e32 v57, 0xffff0000, v152
	v_add_f32_e32 v53, v53, v57
	v_cvt_pk_bf16_f32 v52, v52, v53
	v_lshlrev_b32_e32 v53, 16, v153
	v_add_f32_e32 v53, v54, v53
	v_and_b32_e32 v54, 0xffff0000, v153
	v_add_f32_e32 v54, v55, v54
	v_cvt_pk_bf16_f32 v53, v53, v54
	v_lshlrev_b32_e32 v54, 16, v154
	v_add_f32_e32 v48, v48, v54
	v_and_b32_e32 v54, 0xffff0000, v154
	v_add_f32_e32 v49, v49, v54
	v_cvt_pk_bf16_f32 v54, v48, v49
	v_and_b32_e32 v49, 0xffff0000, v155
	v_lshlrev_b32_e32 v48, 16, v155
	v_add_f32_e32 v49, v51, v49
	v_add_f32_e32 v48, v50, v48
	v_cvt_pk_bf16_f32 v55, v48, v49
	v_and_b32_e32 v49, 0xffff0000, v52
	v_lshlrev_b32_e32 v48, 16, v52
	v_and_b32_e32 v51, 0xffff0000, v53
	v_mul_f32_e32 v49, v49, v49
	v_lshlrev_b32_e32 v50, 16, v53
	v_fmac_f32_e32 v49, v48, v48
	v_mul_f32_e32 v48, v51, v51
	v_and_b32_e32 v58, 0xffff0000, v54
	v_fmac_f32_e32 v48, v50, v50
	v_lshlrev_b32_e32 v57, 16, v54
	v_add_f32_e32 v48, v49, v48
	v_mul_f32_e32 v49, v58, v58
	v_and_b32_e32 v60, 0xffff0000, v55
	v_fmac_f32_e32 v49, v57, v57
	v_lshlrev_b32_e32 v59, 16, v55
	v_add_f32_e32 v48, v48, v49
	v_mul_f32_e32 v49, v60, v60
	v_fmac_f32_e32 v49, v59, v59
	v_add_f32_e32 v48, v48, v49
	v_add_f32_e32 v48, v56, v48
	ds_bpermute_b32 v49, v114, v48
	global_store_dwordx4 v[214:215], v[52:55], off offset:256 sc0 sc1
	s_waitcnt lgkmcnt(0)
	v_add_f32_e32 v48, v48, v49
	ds_bpermute_b32 v49, v115, v48
	s_and_saveexec_b64 s[40:41], s[38:39]
	s_cbranch_execz .LBB0_393
	s_waitcnt lgkmcnt(0)
	v_add_f32_e32 v48, v48, v49
	v_fma_f32 v48, v48, s80, 0.5
	v_trunc_f32_e32 v48, v48
	v_mul_f32_e32 v49, 0x2f800000, v48
	v_floor_f32_e32 v49, v49
	v_fmac_f32_e32 v48, 0xcf800000, v49
	v_cvt_u32_f32_e32 v48, v48
	v_cvt_u32_f32_e32 v49, v49
	global_atomic_add_x2 v[112:113], v[48:49], off offset:1024
; #define PG8_GAS __attribute__((address_space(1)))
; __device__ __forceinline__ unsigned cvt_pk_bf16(float lo, float hi) { unsigned r; asm volatile("v_cvt_pk_bf16_f32 %0, %1, %2" : "=v"(r) : "v"(lo), "v"(hi)); return r; }
;     __device__ __forceinline__ void operator()(const f32x4 (&acc)[2][2][4][2], const Unit& u, int wr, int wc, int fr, int fq) const {
;     ...
;         for (int ai = 0; ai < 2; ++ai)
; #pragma unroll
;             for (int m = 0; m < 4; ++m) { const int row = row0 + ai * HALF + m * 16; PG8_GAS bf16_t* rowb = XBg + (size_t)row * ldc + col0;
;                 float sq = 0.f;
; #pragma unroll
;                 for (int bj = 0; bj < 2; ++bj) { const u32x4 o = pre[ai][m][bj]; const f32x4 c0 = acc[ai][bj][m][0], c1 = acc[ai][bj][m][1];
;                     u32x4 w; w.x = cvt_pk_bf16(__uint_as_float(o.x << 16) + c0[0], __uint_as_float(o.x & 0xffff0000u) + c0[1]); w.y = cvt_pk_bf16(__uint_as_float(o.y << 16) + c0[2], __uint_as_float(o.y & 0xffff0000u) + c0[3]);
;                     w.z = cvt_pk_bf16(__uint_as_float(o.z << 16) + c1[0], __uint_as_float(o.z & 0xffff0000u) + c1[1]); w.w = cvt_pk_bf16(__uint_as_float(o.w << 16) + c1[2], __uint_as_float(o.w & 0xffff0000u) + c1[3]);
;                     *(PG8_GAS u32x4*)(rowb + bj * HALF) = w;
;                     const float a0 = __uint_as_float(w.x << 16), a1 = __uint_as_float(w.x & 0xffff0000u), a2 = __uint_as_float(w.y << 16), a3 = __uint_as_float(w.y & 0xffff0000u);
;                     const float b0 = __uint_as_float(w.z << 16), b1 = __uint_as_float(w.z & 0xffff0000u), b2 = __uint_as_float(w.w << 16), b3 = __uint_as_float(w.w & 0xffff0000u);
;                     sq += (a0 * a0 + a1 * a1) + (a2 * a2 + a3 * a3) + (b0 * b0 + b1 * b1) + (b2 * b2 + b3 * b3); }
;                 sq += __shfl_xor(sq, 16); sq += __shfl_xor(sq, 32);
;                 if (fq == 0) __hip_atomic_fetch_add(ssg + row, (unsigned long long)(sq * 1048576.0f + 0.5f), __ATOMIC_RELAXED, __HIP_MEMORY_SCOPE_AGENT); }
.LBB0_393:
	s_or_b64 exec, exec, s[40:41]
	v_lshlrev_b32_e32 v48, 16, v148
	v_add_f32_e32 v44, v44, v48
	v_and_b32_e32 v48, 0xffff0000, v148
	v_add_f32_e32 v45, v45, v48
	v_cvt_pk_bf16_f32 v44, v44, v45
	v_lshlrev_b32_e32 v45, 16, v149
	v_add_f32_e32 v45, v46, v45
	v_and_b32_e32 v46, 0xffff0000, v149
	v_add_f32_e32 v46, v47, v46
	v_cvt_pk_bf16_f32 v45, v45, v46
	v_lshlrev_b32_e32 v46, 16, v150
	v_add_f32_e32 v40, v40, v46
	v_and_b32_e32 v46, 0xffff0000, v150
	v_add_f32_e32 v41, v41, v46
	v_cvt_pk_bf16_f32 v46, v40, v41
	v_and_b32_e32 v41, 0xffff0000, v151
	v_lshlrev_b32_e32 v40, 16, v151
	v_add_f32_e32 v41, v43, v41
	v_add_f32_e32 v40, v42, v40
	v_cvt_pk_bf16_f32 v47, v40, v41
	v_and_b32_e32 v41, 0xffff0000, v44
	v_lshlrev_b32_e32 v40, 16, v44
	v_and_b32_e32 v43, 0xffff0000, v45
	v_mul_f32_e32 v41, v41, v41
	v_lshlrev_b32_e32 v42, 16, v45
	v_fmac_f32_e32 v41, v40, v40
	v_mul_f32_e32 v40, v43, v43
	global_store_dwordx4 v[212:213], v[44:47], off sc0 sc1
	v_fmac_f32_e32 v40, v42, v42
	v_add_f32_e32 v40, v41, v40
	v_and_b32_e32 v45, 0xffff0000, v46
	v_lshlrev_b32_e32 v44, 16, v46
	v_mul_f32_e32 v41, v45, v45
	v_lshlrev_b32_e32 v46, 16, v47
	v_and_b32_e32 v47, 0xffff0000, v47
	v_fmac_f32_e32 v41, v44, v44
	v_add_f32_e32 v40, v40, v41
	v_mul_f32_e32 v41, v47, v47
	v_fmac_f32_e32 v41, v46, v46
	v_add_f32_e32 v40, v40, v41
	v_lshlrev_b32_e32 v41, 16, v144
	v_add_f32_e32 v36, v36, v41
	v_and_b32_e32 v41, 0xffff0000, v144
	v_add_f32_e32 v37, v37, v41
	v_cvt_pk_bf16_f32 v36, v36, v37
	v_lshlrev_b32_e32 v37, 16, v145
	v_add_f32_e32 v37, v38, v37
	v_and_b32_e32 v38, 0xffff0000, v145
	v_add_f32_e32 v38, v39, v38
	v_cvt_pk_bf16_f32 v37, v37, v38
	v_lshlrev_b32_e32 v38, 16, v146
	v_add_f32_e32 v32, v32, v38
	v_and_b32_e32 v38, 0xffff0000, v146
	v_add_f32_e32 v33, v33, v38
	v_cvt_pk_bf16_f32 v38, v32, v33
	v_and_b32_e32 v33, 0xffff0000, v147
	v_lshlrev_b32_e32 v32, 16, v147
	v_add_f32_e32 v33, v35, v33
	v_add_f32_e32 v32, v34, v32
	v_cvt_pk_bf16_f32 v39, v32, v33
	v_and_b32_e32 v33, 0xffff0000, v36
	v_lshlrev_b32_e32 v32, 16, v36
	v_and_b32_e32 v35, 0xffff0000, v37
	v_mul_f32_e32 v33, v33, v33
	v_lshlrev_b32_e32 v34, 16, v37
	v_fmac_f32_e32 v33, v32, v32
	v_mul_f32_e32 v32, v35, v35
	v_and_b32_e32 v42, 0xffff0000, v38
	v_fmac_f32_e32 v32, v34, v34
	v_lshlrev_b32_e32 v41, 16, v38
	v_add_f32_e32 v32, v33, v32
	v_mul_f32_e32 v33, v42, v42
	v_and_b32_e32 v44, 0xffff0000, v39
	v_fmac_f32_e32 v33, v41, v41
	v_lshlrev_b32_e32 v43, 16, v39
	v_add_f32_e32 v32, v32, v33
	v_mul_f32_e32 v33, v44, v44
	v_fmac_f32_e32 v33, v43, v43
	v_add_f32_e32 v32, v32, v33
	v_add_f32_e32 v32, v40, v32
	ds_bpermute_b32 v33, v114, v32
	global_store_dwordx4 v[212:213], v[36:39], off offset:256 sc0 sc1
	s_waitcnt lgkmcnt(0)
	v_add_f32_e32 v32, v32, v33
	ds_bpermute_b32 v33, v115, v32
	s_and_saveexec_b64 s[40:41], s[38:39]
	s_cbranch_execz .LBB0_395
	s_waitcnt lgkmcnt(0)
	v_add_f32_e32 v32, v32, v33
	v_fma_f32 v32, v32, s80, 0.5
	v_trunc_f32_e32 v32, v32
	v_mul_f32_e32 v33, 0x2f800000, v32
	v_floor_f32_e32 v33, v33
	v_fmac_f32_e32 v32, 0xcf800000, v33
	v_cvt_u32_f32_e32 v32, v32
	v_cvt_u32_f32_e32 v33, v33
	global_atomic_add_x2 v[112:113], v[32:33], off offset:1152
; #define PG8_GAS __attribute__((address_space(1)))
; __device__ __forceinline__ unsigned cvt_pk_bf16(float lo, float hi) { unsigned r; asm volatile("v_cvt_pk_bf16_f32 %0, %1, %2" : "=v"(r) : "v"(lo), "v"(hi)); return r; }
;     __device__ __forceinline__ void operator()(const f32x4 (&acc)[2][2][4][2], const Unit& u, int wr, int wc, int fr, int fq) const {
;     ...
;         for (int ai = 0; ai < 2; ++ai)
; #pragma unroll
;             for (int m = 0; m < 4; ++m) { const int row = row0 + ai * HALF + m * 16; PG8_GAS bf16_t* rowb = XBg + (size_t)row * ldc + col0;
;                 float sq = 0.f;
; #pragma unroll
;                 for (int bj = 0; bj < 2; ++bj) { const u32x4 o = pre[ai][m][bj]; const f32x4 c0 = acc[ai][bj][m][0], c1 = acc[ai][bj][m][1];
;                     u32x4 w; w.x = cvt_pk_bf16(__uint_as_float(o.x << 16) + c0[0], __uint_as_float(o.x & 0xffff0000u) + c0[1]); w.y = cvt_pk_bf16(__uint_as_float(o.y << 16) + c0[2], __uint_as_float(o.y & 0xffff0000u) + c0[3]);
;                     w.z = cvt_pk_bf16(__uint_as_float(o.z << 16) + c1[0], __uint_as_float(o.z & 0xffff0000u) + c1[1]); w.w = cvt_pk_bf16(__uint_as_float(o.w << 16) + c1[2], __uint_as_float(o.w & 0xffff0000u) + c1[3]);
;                     *(PG8_GAS u32x4*)(rowb + bj * HALF) = w;
;                     const float a0 = __uint_as_float(w.x << 16), a1 = __uint_as_float(w.x & 0xffff0000u), a2 = __uint_as_float(w.y << 16), a3 = __uint_as_float(w.y & 0xffff0000u);
;                     const float b0 = __uint_as_float(w.z << 16), b1 = __uint_as_float(w.z & 0xffff0000u), b2 = __uint_as_float(w.w << 16), b3 = __uint_as_float(w.w & 0xffff0000u);
;                     sq += (a0 * a0 + a1 * a1) + (a2 * a2 + a3 * a3) + (b0 * b0 + b1 * b1) + (b2 * b2 + b3 * b3); }
;                 sq += __shfl_xor(sq, 16); sq += __shfl_xor(sq, 32);
;                 if (fq == 0) __hip_atomic_fetch_add(ssg + row, (unsigned long long)(sq * 1048576.0f + 0.5f), __ATOMIC_RELAXED, __HIP_MEMORY_SCOPE_AGENT); }
.LBB0_395:
	s_or_b64 exec, exec, s[40:41]
	v_lshlrev_b32_e32 v32, 16, v140
	v_add_f32_e32 v28, v28, v32
	v_and_b32_e32 v32, 0xffff0000, v140
	v_add_f32_e32 v29, v29, v32
	v_cvt_pk_bf16_f32 v28, v28, v29
	v_lshlrev_b32_e32 v29, 16, v141
	v_add_f32_e32 v29, v30, v29
	v_and_b32_e32 v30, 0xffff0000, v141
	v_add_f32_e32 v30, v31, v30
	v_cvt_pk_bf16_f32 v29, v29, v30
	v_lshlrev_b32_e32 v30, 16, v142
	v_add_f32_e32 v24, v24, v30
	v_and_b32_e32 v30, 0xffff0000, v142
	v_add_f32_e32 v25, v25, v30
	v_cvt_pk_bf16_f32 v30, v24, v25
	v_and_b32_e32 v25, 0xffff0000, v143
	v_lshlrev_b32_e32 v24, 16, v143
	v_add_f32_e32 v25, v27, v25
	v_add_f32_e32 v24, v26, v24
	v_cvt_pk_bf16_f32 v31, v24, v25
	v_and_b32_e32 v25, 0xffff0000, v28
	v_lshlrev_b32_e32 v24, 16, v28
	v_and_b32_e32 v27, 0xffff0000, v29
	v_mul_f32_e32 v25, v25, v25
	v_lshlrev_b32_e32 v26, 16, v29
	v_fmac_f32_e32 v25, v24, v24
	v_mul_f32_e32 v24, v27, v27
	global_store_dwordx4 v[210:211], v[28:31], off sc0 sc1
	v_fmac_f32_e32 v24, v26, v26
	v_add_f32_e32 v24, v25, v24
	v_and_b32_e32 v29, 0xffff0000, v30
	v_lshlrev_b32_e32 v28, 16, v30
	v_mul_f32_e32 v25, v29, v29
	v_lshlrev_b32_e32 v30, 16, v31
	v_and_b32_e32 v31, 0xffff0000, v31
	v_fmac_f32_e32 v25, v28, v28
	v_add_f32_e32 v24, v24, v25
	v_mul_f32_e32 v25, v31, v31
	v_fmac_f32_e32 v25, v30, v30
	v_add_f32_e32 v24, v24, v25
	v_lshlrev_b32_e32 v25, 16, v128
	v_add_f32_e32 v20, v20, v25
	v_and_b32_e32 v25, 0xffff0000, v128
	v_add_f32_e32 v21, v21, v25
	v_cvt_pk_bf16_f32 v20, v20, v21
	v_lshlrev_b32_e32 v21, 16, v129
	v_add_f32_e32 v21, v22, v21
	v_and_b32_e32 v22, 0xffff0000, v129
	v_add_f32_e32 v22, v23, v22
	v_cvt_pk_bf16_f32 v21, v21, v22
	v_lshlrev_b32_e32 v22, 16, v130
	v_add_f32_e32 v16, v16, v22
	v_and_b32_e32 v22, 0xffff0000, v130
	v_add_f32_e32 v17, v17, v22
	v_cvt_pk_bf16_f32 v22, v16, v17
	v_and_b32_e32 v17, 0xffff0000, v131
	v_lshlrev_b32_e32 v16, 16, v131
	v_add_f32_e32 v17, v19, v17
	v_add_f32_e32 v16, v18, v16
	v_cvt_pk_bf16_f32 v23, v16, v17
	v_and_b32_e32 v17, 0xffff0000, v20
	v_lshlrev_b32_e32 v16, 16, v20
	v_and_b32_e32 v19, 0xffff0000, v21
	v_mul_f32_e32 v17, v17, v17
	v_lshlrev_b32_e32 v18, 16, v21
	v_fmac_f32_e32 v17, v16, v16
	v_mul_f32_e32 v16, v19, v19
	v_and_b32_e32 v26, 0xffff0000, v22
	v_fmac_f32_e32 v16, v18, v18
	v_lshlrev_b32_e32 v25, 16, v22
	v_add_f32_e32 v16, v17, v16
	v_mul_f32_e32 v17, v26, v26
	v_and_b32_e32 v28, 0xffff0000, v23
	v_fmac_f32_e32 v17, v25, v25
	v_lshlrev_b32_e32 v27, 16, v23
	v_add_f32_e32 v16, v16, v17
	v_mul_f32_e32 v17, v28, v28
	v_fmac_f32_e32 v17, v27, v27
	v_add_f32_e32 v16, v16, v17
	v_add_f32_e32 v16, v24, v16
	ds_bpermute_b32 v17, v114, v16
	global_store_dwordx4 v[210:211], v[20:23], off offset:256 sc0 sc1
	s_waitcnt lgkmcnt(0)
	v_add_f32_e32 v16, v16, v17
	ds_bpermute_b32 v17, v115, v16
	s_and_saveexec_b64 s[40:41], s[38:39]
	s_cbranch_execz .LBB0_397
	s_waitcnt lgkmcnt(0)
	v_add_f32_e32 v16, v16, v17
	v_fma_f32 v16, v16, s80, 0.5
	v_trunc_f32_e32 v16, v16
	v_mul_f32_e32 v17, 0x2f800000, v16
	v_floor_f32_e32 v17, v17
	v_fmac_f32_e32 v16, 0xcf800000, v17
	v_cvt_u32_f32_e32 v16, v16
	v_cvt_u32_f32_e32 v17, v17
	global_atomic_add_x2 v[112:113], v[16:17], off offset:1280
.LBB0_397:
	s_or_b64 exec, exec, s[40:41]
	s_waitcnt vmcnt(15)
	v_lshlrev_b32_e32 v16, 16, v132
	v_add_f32_e32 v12, v12, v16
	v_and_b32_e32 v16, 0xffff0000, v132
	v_add_f32_e32 v13, v13, v16
	v_cvt_pk_bf16_f32 v12, v12, v13
	v_lshlrev_b32_e32 v13, 16, v133
	v_add_f32_e32 v13, v14, v13
	v_and_b32_e32 v14, 0xffff0000, v133
	v_add_f32_e32 v14, v15, v14
	v_cvt_pk_bf16_f32 v13, v13, v14
	v_lshlrev_b32_e32 v14, 16, v134
	v_add_f32_e32 v8, v8, v14
	v_and_b32_e32 v14, 0xffff0000, v134
	v_add_f32_e32 v9, v9, v14
	v_cvt_pk_bf16_f32 v14, v8, v9
	v_and_b32_e32 v9, 0xffff0000, v135
	v_lshlrev_b32_e32 v8, 16, v135
	v_add_f32_e32 v9, v11, v9
	v_add_f32_e32 v8, v10, v8
	v_cvt_pk_bf16_f32 v15, v8, v9
	v_and_b32_e32 v9, 0xffff0000, v12
	v_lshlrev_b32_e32 v8, 16, v12
	v_and_b32_e32 v11, 0xffff0000, v13
	v_mul_f32_e32 v9, v9, v9
	v_lshlrev_b32_e32 v10, 16, v13
	v_fmac_f32_e32 v9, v8, v8
	v_mul_f32_e32 v8, v11, v11
	global_store_dwordx4 v[208:209], v[12:15], off sc0 sc1
	v_fmac_f32_e32 v8, v10, v10
	v_add_f32_e32 v8, v9, v8
	v_and_b32_e32 v13, 0xffff0000, v14
	v_lshlrev_b32_e32 v12, 16, v14
	v_mul_f32_e32 v9, v13, v13
	v_lshlrev_b32_e32 v14, 16, v15
	v_and_b32_e32 v15, 0xffff0000, v15
	v_fmac_f32_e32 v9, v12, v12
	v_add_f32_e32 v8, v8, v9
	v_mul_f32_e32 v9, v15, v15
	v_fmac_f32_e32 v9, v14, v14
	v_add_f32_e32 v8, v8, v9
	s_waitcnt vmcnt(15)
	v_lshlrev_b32_e32 v9, 16, v124
	v_add_f32_e32 v4, v4, v9
	v_and_b32_e32 v9, 0xffff0000, v124
	v_add_f32_e32 v5, v5, v9
	v_cvt_pk_bf16_f32 v4, v4, v5
	v_lshlrev_b32_e32 v5, 16, v125
	v_add_f32_e32 v5, v6, v5
	v_and_b32_e32 v6, 0xffff0000, v125
	v_add_f32_e32 v6, v7, v6
	v_cvt_pk_bf16_f32 v5, v5, v6
	v_lshlrev_b32_e32 v6, 16, v126
	v_add_f32_e32 v0, v0, v6
	v_and_b32_e32 v6, 0xffff0000, v126
	v_add_f32_e32 v1, v1, v6
	v_cvt_pk_bf16_f32 v6, v0, v1
	v_and_b32_e32 v1, 0xffff0000, v127
	v_lshlrev_b32_e32 v0, 16, v127
	v_add_f32_e32 v1, v3, v1
	v_add_f32_e32 v0, v2, v0
	v_cvt_pk_bf16_f32 v7, v0, v1
	v_and_b32_e32 v1, 0xffff0000, v4
	v_lshlrev_b32_e32 v0, 16, v4
	v_and_b32_e32 v3, 0xffff0000, v5
	v_mul_f32_e32 v1, v1, v1
	v_lshlrev_b32_e32 v2, 16, v5
	v_fmac_f32_e32 v1, v0, v0
	v_mul_f32_e32 v0, v3, v3
	v_and_b32_e32 v10, 0xffff0000, v6
	v_fmac_f32_e32 v0, v2, v2
	v_lshlrev_b32_e32 v9, 16, v6
	v_add_f32_e32 v0, v1, v0
	v_mul_f32_e32 v1, v10, v10
	v_and_b32_e32 v12, 0xffff0000, v7
	v_fmac_f32_e32 v1, v9, v9
	v_lshlrev_b32_e32 v11, 16, v7
	v_add_f32_e32 v0, v0, v1
	v_mul_f32_e32 v1, v12, v12
	v_fmac_f32_e32 v1, v11, v11
	v_add_f32_e32 v0, v0, v1
	v_add_f32_e32 v0, v8, v0
	ds_bpermute_b32 v1, v114, v0
	global_store_dwordx4 v[208:209], v[4:7], off offset:256 sc0 sc1
	s_waitcnt lgkmcnt(0)
	v_add_f32_e32 v0, v0, v1
	ds_bpermute_b32 v1, v115, v0
	s_and_saveexec_b64 s[40:41], s[38:39]
	s_cbranch_execz .LBB0_399
	s_waitcnt lgkmcnt(0)
	v_add_f32_e32 v0, v0, v1
	v_fma_f32 v0, v0, s80, 0.5
	v_trunc_f32_e32 v0, v0
	v_mul_f32_e32 v1, 0x2f800000, v0
	v_floor_f32_e32 v1, v1
	v_fmac_f32_e32 v0, 0xcf800000, v1
	v_cvt_u32_f32_e32 v0, v0
	v_cvt_u32_f32_e32 v1, v1
	global_atomic_add_x2 v[112:113], v[0:1], off offset:1408
